# RWKV scan chunk 8-byte aligned (4-byte instructions only in adjacent pairs, .p2alignl at the chunk head), tiles as before
# speedup vs baseline: 1.0084x; 1.0061x over previous
; #define LAS __attribute__((address_space(3)))
; template <bool SAMPLE>
; __device__ __forceinline__ void rwkv_unit(PR P, LAS float* lds, const int b, const int h, const int half, const int wv) {
;     ...
;     for (int c = 0; c < NCH; ++c) {
;         LAS float* cur = (c & 1) ? buf1 : buf0; LAS float* nxt = (c & 1) ? buf0 : buf1;
;         if (c + 1 < NCH) RW_LOAD(c + 1);
;         if (wid < 4) {
;             constexpr int GS = SAMPLE ? 4 : 16;
;             for (int g = 0; g < TC / GS; ++g) {
;                 float yk0 = 0.f, yk1 = 0.f;
;                 const LAS float* q0 = cur + (g * GS) * 384;
;                 f32x4 r4 = *(const LAS f32x4*)(q0 + j0), o4 = *(const LAS f32x4*)(q0 + 64 + j0), k4 = *(const LAS f32x4*)(q0 + 128 + j0), a4 = *(const LAS f32x4*)(q0 + 192 + j0), b4 = *(const LAS f32x4*)(q0 + 256 + j0);
;                 f32x2 v2 = *(const LAS f32x2*)(q0 + 320 + row0);
;                 float py0 = 0.f, py1 = 0.f;
; #pragma unroll
;                 for (int tt = 0; tt < GS; ++tt) {
;                     const LAS float* qn = q0 + (tt + 1 < GS ? tt + 1 : tt) * 384;
;                     const f32x4 nr4 = *(const LAS f32x4*)(qn + j0), no4 = *(const LAS f32x4*)(qn + 64 + j0), nk4 = *(const LAS f32x4*)(qn + 128 + j0), na4 = *(const LAS f32x4*)(qn + 192 + j0), nb4 = *(const LAS f32x4*)(qn + 256 + j0);
;                     const f32x2 nv2 = *(const LAS f32x2*)(qn + 320 + row0);
;                     f32x2 sa = (S[0] * a4[0] + S[1] * a4[1]) + (S[2] * a4[2] + S[3] * a4[3]);
;                     float sx = sa.x, sy = sa.y; ROW16_SUM4(sx, sy, py0, py1); sa = (f32x2){sx, sy};
;                     if (tt > 0) { yk0 = cgl == tt - 1 ? py0 : yk0; yk1 = cgl == tt - 1 ? py1 : yk1; }
; #pragma unroll
;                     for (int c = 0; c < 4; ++c) { f32x2 t = S[c] - S[c] * o4[c]; t = t + sa * b4[c]; S[c] = t + v2 * k4[c]; }
;                     const f32x2 y = (S[0] * r4[0] + S[1] * r4[1]) + (S[2] * r4[2] + S[3] * r4[3]);
;                     py0 = y.x; py1 = y.y;
;                     r4 = nr4; o4 = no4; k4 = nk4; a4 = na4; b4 = nb4; v2 = nv2;
;                 }
;                 ROW16_SUM2(py0, py1); yk0 = cgl == GS - 1 ? py0 : yk0; yk1 = cgl == GS - 1 ? py1 : yk1;
;                 if (cgl < GS) *(unsigned*)(YS + (size_t)(row_base + c * TC + g * GS + cgl) * 512 + h * 64 + row0) = pg8::cvt_pk_bf16(yk0, yk1);
.Lrw_scan_chunk:
	s_add_i32 s56, s71, 1
	s_bitcmp0_b32 s71, 0
	s_cselect_b32 s57, 0, s55
	v_lshl_add_u32 v57, s71, 5, v77
	.p2alignl 3, 3212836864
	v_lshl_add_u32 v152, v76, 2, s57
	v_lshl_add_u32 v153, v54, 2, s57
	v_add_u32_e32 v153, 0x100, v153
	ds_read_b128 v[172:175], v152 offset:768
	ds_read_b128 v[164:167], v152 offset:256
	ds_read2st64_b64 v[240:243], v153 offset0:2 offset1:5
	ds_read_b128 v[168:171], v152 offset:512
	ds_read_b128 v[192:195], v152 offset:2304
	ds_read_b128 v[184:187], v152 offset:1792
	ds_read_b128 v[176:179], v152 offset:1024
	ds_read_b128 v[188:191], v152 offset:2048
	ds_read_b128 v[196:199], v152 offset:2560
	ds_read_b128 v[160:163], v152 offset:0
	ds_read_b128 v[180:183], v152 offset:1536
	s_cmp_eq_u32 s71, 0
	s_cbranch_scc1 .Lrw_first_chunk
	v_add_f32_dpp v110, v110, v110 row_ror:8 row_mask:0xf bank_mask:0x3 bound_ctrl:1
	v_add_f32_dpp v110, v126, v126 row_ror:8 row_mask:0xf bank_mask:0xc bound_ctrl:1
	v_add_f32_dpp v112, v112, v112 row_ror:8 row_mask:0xf bank_mask:0x3 bound_ctrl:1
	v_add_f32_dpp v112, v128, v128 row_ror:8 row_mask:0xf bank_mask:0xc bound_ctrl:1
	v_add_f32_dpp v114, v114, v114 row_ror:8 row_mask:0xf bank_mask:0x3 bound_ctrl:1
	v_add_f32_dpp v114, v130, v130 row_ror:8 row_mask:0xf bank_mask:0xc bound_ctrl:1
	v_add_f32_dpp v116, v116, v116 row_ror:8 row_mask:0xf bank_mask:0x3 bound_ctrl:1
	v_add_f32_dpp v116, v132, v132 row_ror:8 row_mask:0xf bank_mask:0xc bound_ctrl:1
	v_add_f32_dpp v118, v118, v118 row_ror:8 row_mask:0xf bank_mask:0x3 bound_ctrl:1
	v_add_f32_dpp v118, v134, v134 row_ror:8 row_mask:0xf bank_mask:0xc bound_ctrl:1
	v_add_f32_dpp v120, v120, v120 row_ror:8 row_mask:0xf bank_mask:0x3 bound_ctrl:1
	v_add_f32_dpp v120, v136, v136 row_ror:8 row_mask:0xf bank_mask:0xc bound_ctrl:1
	v_add_f32_dpp v122, v122, v122 row_ror:8 row_mask:0xf bank_mask:0x3 bound_ctrl:1
	v_add_f32_dpp v122, v138, v138 row_ror:8 row_mask:0xf bank_mask:0xc bound_ctrl:1
	v_add_f32_dpp v124, v124, v124 row_ror:8 row_mask:0xf bank_mask:0x3 bound_ctrl:1
	v_add_f32_dpp v124, v140, v140 row_ror:8 row_mask:0xf bank_mask:0xc bound_ctrl:1
	v_add_f32_dpp v111, v111, v111 row_ror:8 row_mask:0xf bank_mask:0x3 bound_ctrl:1
	v_add_f32_dpp v111, v127, v127 row_ror:8 row_mask:0xf bank_mask:0xc bound_ctrl:1
	v_add_f32_dpp v113, v113, v113 row_ror:8 row_mask:0xf bank_mask:0x3 bound_ctrl:1
	v_add_f32_dpp v113, v129, v129 row_ror:8 row_mask:0xf bank_mask:0xc bound_ctrl:1
	v_add_f32_dpp v115, v115, v115 row_ror:8 row_mask:0xf bank_mask:0x3 bound_ctrl:1
	v_add_f32_dpp v115, v131, v131 row_ror:8 row_mask:0xf bank_mask:0xc bound_ctrl:1
	v_add_f32_dpp v117, v117, v117 row_ror:8 row_mask:0xf bank_mask:0x3 bound_ctrl:1
	v_add_f32_dpp v117, v133, v133 row_ror:8 row_mask:0xf bank_mask:0xc bound_ctrl:1
	v_add_f32_dpp v119, v119, v119 row_ror:8 row_mask:0xf bank_mask:0x3 bound_ctrl:1
	v_add_f32_dpp v119, v135, v135 row_ror:8 row_mask:0xf bank_mask:0xc bound_ctrl:1
	v_add_f32_dpp v121, v121, v121 row_ror:8 row_mask:0xf bank_mask:0x3 bound_ctrl:1
	v_add_f32_dpp v121, v137, v137 row_ror:8 row_mask:0xf bank_mask:0xc bound_ctrl:1
	v_add_f32_dpp v123, v123, v123 row_ror:8 row_mask:0xf bank_mask:0x3 bound_ctrl:1
	v_add_f32_dpp v123, v139, v139 row_ror:8 row_mask:0xf bank_mask:0xc bound_ctrl:1
	v_add_f32_dpp v125, v125, v125 row_ror:8 row_mask:0xf bank_mask:0x3 bound_ctrl:1
	v_add_f32_dpp v125, v141, v141 row_ror:8 row_mask:0xf bank_mask:0xc bound_ctrl:1
	v_add_f32_dpp v110, v110, v110 row_shl:4 row_mask:0xf bank_mask:0x5 bound_ctrl:1
	v_add_f32_dpp v110, v118, v118 row_shr:4 row_mask:0xf bank_mask:0xa bound_ctrl:1
	v_add_f32_dpp v112, v112, v112 row_shl:4 row_mask:0xf bank_mask:0x5 bound_ctrl:1
	v_add_f32_dpp v112, v120, v120 row_shr:4 row_mask:0xf bank_mask:0xa bound_ctrl:1
	v_add_f32_dpp v114, v114, v114 row_shl:4 row_mask:0xf bank_mask:0x5 bound_ctrl:1
	v_add_f32_dpp v114, v122, v122 row_shr:4 row_mask:0xf bank_mask:0xa bound_ctrl:1
	v_add_f32_dpp v116, v116, v116 row_shl:4 row_mask:0xf bank_mask:0x5 bound_ctrl:1
	v_add_f32_dpp v116, v124, v124 row_shr:4 row_mask:0xf bank_mask:0xa bound_ctrl:1
	v_add_f32_dpp v111, v111, v111 row_shl:4 row_mask:0xf bank_mask:0x5 bound_ctrl:1
	v_add_f32_dpp v111, v119, v119 row_shr:4 row_mask:0xf bank_mask:0xa bound_ctrl:1
	v_add_f32_dpp v113, v113, v113 row_shl:4 row_mask:0xf bank_mask:0x5 bound_ctrl:1
	v_add_f32_dpp v113, v121, v121 row_shr:4 row_mask:0xf bank_mask:0xa bound_ctrl:1
	v_add_f32_dpp v115, v115, v115 row_shl:4 row_mask:0xf bank_mask:0x5 bound_ctrl:1
	v_add_f32_dpp v115, v123, v123 row_shr:4 row_mask:0xf bank_mask:0xa bound_ctrl:1
	v_add_f32_dpp v117, v117, v117 row_shl:4 row_mask:0xf bank_mask:0x5 bound_ctrl:1
	v_add_f32_dpp v117, v125, v125 row_shr:4 row_mask:0xf bank_mask:0xa bound_ctrl:1
	v_add_f32_dpp v110, v110, v110 quad_perm:[1,0,3,2] row_mask:0xf bank_mask:0xf bound_ctrl:1
	v_add_f32_dpp v112, v112, v112 quad_perm:[1,0,3,2] row_mask:0xf bank_mask:0xf bound_ctrl:1
	v_add_f32_dpp v114, v114, v114 quad_perm:[1,0,3,2] row_mask:0xf bank_mask:0xf bound_ctrl:1
	v_add_f32_dpp v116, v116, v116 quad_perm:[1,0,3,2] row_mask:0xf bank_mask:0xf bound_ctrl:1
	v_add_f32_dpp v111, v111, v111 quad_perm:[1,0,3,2] row_mask:0xf bank_mask:0xf bound_ctrl:1
	v_add_f32_dpp v113, v113, v113 quad_perm:[1,0,3,2] row_mask:0xf bank_mask:0xf bound_ctrl:1
	v_add_f32_dpp v115, v115, v115 quad_perm:[1,0,3,2] row_mask:0xf bank_mask:0xf bound_ctrl:1
	v_add_f32_dpp v117, v117, v117 quad_perm:[1,0,3,2] row_mask:0xf bank_mask:0xf bound_ctrl:1
	v_add_f32_dpp v110, v110, v110 quad_perm:[2,3,0,1] row_mask:0xf bank_mask:0xf bound_ctrl:1
	v_add_f32_dpp v112, v112, v112 quad_perm:[2,3,0,1] row_mask:0xf bank_mask:0xf bound_ctrl:1
	v_add_f32_dpp v114, v114, v114 quad_perm:[2,3,0,1] row_mask:0xf bank_mask:0xf bound_ctrl:1
	v_add_f32_dpp v116, v116, v116 quad_perm:[2,3,0,1] row_mask:0xf bank_mask:0xf bound_ctrl:1
	v_add_f32_dpp v111, v111, v111 quad_perm:[2,3,0,1] row_mask:0xf bank_mask:0xf bound_ctrl:1
	v_add_f32_dpp v113, v113, v113 quad_perm:[2,3,0,1] row_mask:0xf bank_mask:0xf bound_ctrl:1
	v_add_f32_dpp v115, v115, v115 quad_perm:[2,3,0,1] row_mask:0xf bank_mask:0xf bound_ctrl:1
	v_add_f32_dpp v117, v117, v117 quad_perm:[2,3,0,1] row_mask:0xf bank_mask:0xf bound_ctrl:1
	v_subrev_u32_e32 v72, 16, v57
	v_ashrrev_i32_e32 v73, 31, v72
	v_lshlrev_b64 v[72:73], 10, v[72:73]
	v_lshl_add_u64 v[72:73], v[64:65], 0, v[72:73]
	v_cndmask_b32_e64 v154, v116, v114, s[16:17]
	v_cndmask_b32_e64 v155, v117, v115, s[16:17]
	v_cndmask_b32_e64 v154, v154, v112, s[14:15]
	v_cndmask_b32_e64 v155, v155, v113, s[14:15]
	v_cndmask_b32_e64 v154, v154, v110, s[12:13]
	v_cndmask_b32_e64 v155, v155, v111, s[12:13]
	v_cvt_pk_bf16_f32 v154, v154, v155
	global_store_dword v[72:73], v154, off
; #define LAS __attribute__((address_space(3)))
; #define ROW16_SUM4(x, y, z, w) do { DPP4(x, y, z, w, "quad_perm:[1,0,3,2]", "s_nop 1"); DPP4(x, y, z, w, "quad_perm:[2,3,0,1]", ""); DPP4(x, y, z, w, "row_half_mirror", ""); DPP4(x, y, z, w, "row_mirror", ""); } while (0)
; template <bool SAMPLE>
; __device__ __forceinline__ void rwkv_unit(PR P, LAS float* lds, const int b, const int h, const int half, const int wv) {
;     ...
;                 for (int tt = 0; tt < GS; ++tt) {
;                     const LAS float* qn = q0 + (tt + 1 < GS ? tt + 1 : tt) * 384;
;                     const f32x4 nr4 = *(const LAS f32x4*)(qn + j0), no4 = *(const LAS f32x4*)(qn + 64 + j0), nk4 = *(const LAS f32x4*)(qn + 128 + j0), na4 = *(const LAS f32x4*)(qn + 192 + j0), nb4 = *(const LAS f32x4*)(qn + 256 + j0);
;                     const f32x2 nv2 = *(const LAS f32x2*)(qn + 320 + row0);
;                     f32x2 sa = (S[0] * a4[0] + S[1] * a4[1]) + (S[2] * a4[2] + S[3] * a4[3]);
;                     float sx = sa.x, sy = sa.y; ROW16_SUM4(sx, sy, py0, py1); sa = (f32x2){sx, sy};
;                     if (tt > 0) { yk0 = cgl == tt - 1 ? py0 : yk0; yk1 = cgl == tt - 1 ? py1 : yk1; }
; #pragma unroll
;                     for (int c = 0; c < 4; ++c) { f32x2 t = S[c] - S[c] * o4[c]; t = t + sa * b4[c]; S[c] = t + v2 * k4[c]; }
;                     const f32x2 y = (S[0] * r4[0] + S[1] * r4[1]) + (S[2] * r4[2] + S[3] * r4[3]);
;                     py0 = y.x; py1 = y.y;
;                     r4 = nr4; o4 = no4; k4 = nk4; a4 = na4; b4 = nb4; v2 = nv2;
.Lrw_first_chunk:
	s_waitcnt lgkmcnt(0)
	s_nop 0
	v_pk_mul_f32 v[150:151], v[66:67], v[172:173] op_sel_hi:[1,0]
	v_pk_fma_f32 v[142:143], v[66:67], v[164:165], v[66:67] op_sel_hi:[1,0,1] neg_lo:[1,0,0] neg_hi:[1,0,0]
	ds_read_b128 v[212:215], v152 offset:3840
	v_pk_fma_f32 v[150:151], v[20:21], v[172:173], v[150:151] op_sel:[0,1,0]
	v_pk_fma_f32 v[144:145], v[20:21], v[164:165], v[20:21] op_sel:[0,1,0] neg_lo:[1,0,0] neg_hi:[1,0,0]
	ds_read_b128 v[204:207], v152 offset:3328
	v_pk_fma_f32 v[150:151], v[68:69], v[174:175], v[150:151] op_sel_hi:[1,0,1]
	v_pk_fma_f32 v[146:147], v[68:69], v[166:167], v[68:69] op_sel_hi:[1,0,1] neg_lo:[1,0,0] neg_hi:[1,0,0]
	ds_read2st64_b64 v[244:247], v153 offset0:8 offset1:11
	v_pk_fma_f32 v[150:151], v[70:71], v[174:175], v[150:151] op_sel:[0,1,0]
	v_pk_fma_f32 v[148:149], v[70:71], v[166:167], v[70:71] op_sel:[0,1,0] neg_lo:[1,0,0] neg_hi:[1,0,0]
	ds_read_b128 v[208:211], v152 offset:3584
	v_pk_fma_f32 v[142:143], v[240:241], v[168:169], v[142:143] op_sel_hi:[1,0,1]
	v_pk_fma_f32 v[144:145], v[240:241], v[168:169], v[144:145] op_sel:[0,1,0]
	v_add_f32_dpp v150, v150, v150 quad_perm:[1,0,3,2] row_mask:0xf bank_mask:0xf bound_ctrl:1
	v_add_f32_dpp v151, v151, v151 quad_perm:[1,0,3,2] row_mask:0xf bank_mask:0xf bound_ctrl:1
	v_pk_fma_f32 v[146:147], v[240:241], v[170:171], v[146:147] op_sel_hi:[1,0,1]
	v_add_f32_dpp v150, v150, v150 quad_perm:[2,3,0,1] row_mask:0xf bank_mask:0xf bound_ctrl:1
	v_add_f32_dpp v151, v151, v151 quad_perm:[2,3,0,1] row_mask:0xf bank_mask:0xf bound_ctrl:1
	v_pk_fma_f32 v[148:149], v[240:241], v[170:171], v[148:149] op_sel:[0,1,0]
	v_add_f32_dpp v150, v150, v150 row_half_mirror row_mask:0xf bank_mask:0xf bound_ctrl:1
	v_add_f32_dpp v151, v151, v151 row_half_mirror row_mask:0xf bank_mask:0xf bound_ctrl:1
	ds_read_b128 v[232:235], v152 offset:5376
	v_add_f32_dpp v150, v150, v150 row_mirror row_mask:0xf bank_mask:0xf bound_ctrl:1
	v_add_f32_dpp v151, v151, v151 row_mirror row_mask:0xf bank_mask:0xf bound_ctrl:1
	ds_read_b128 v[224:227], v152 offset:4864
	ds_read_b128 v[216:219], v152 offset:4096
	ds_read_b128 v[228:231], v152 offset:5120
	ds_read_b128 v[236:239], v152 offset:5632
	ds_read_b128 v[200:203], v152 offset:3072
	ds_read_b128 v[220:223], v152 offset:4608
	v_pk_fma_f32 v[66:67], v[150:151], v[176:177], v[142:143] op_sel_hi:[1,0,1]
	v_pk_fma_f32 v[20:21], v[150:151], v[176:177], v[144:145] op_sel:[0,1,0]
	v_pk_fma_f32 v[68:69], v[150:151], v[178:179], v[146:147] op_sel_hi:[1,0,1]
	v_pk_fma_f32 v[70:71], v[150:151], v[178:179], v[148:149] op_sel:[0,1,0]
	v_pk_mul_f32 v[78:79], v[66:67], v[160:161] op_sel_hi:[1,0]
	v_pk_mul_f32 v[150:151], v[66:67], v[192:193] op_sel_hi:[1,0]
	v_pk_fma_f32 v[142:143], v[66:67], v[184:185], v[66:67] op_sel_hi:[1,0,1] neg_lo:[1,0,0] neg_hi:[1,0,0]
	v_pk_fma_f32 v[78:79], v[20:21], v[160:161], v[78:79] op_sel:[0,1,0]
	v_pk_fma_f32 v[150:151], v[20:21], v[192:193], v[150:151] op_sel:[0,1,0]
	v_pk_fma_f32 v[144:145], v[20:21], v[184:185], v[20:21] op_sel:[0,1,0] neg_lo:[1,0,0] neg_hi:[1,0,0]
	v_pk_fma_f32 v[78:79], v[68:69], v[162:163], v[78:79] op_sel_hi:[1,0,1]
	v_pk_fma_f32 v[150:151], v[68:69], v[194:195], v[150:151] op_sel_hi:[1,0,1]
	v_pk_fma_f32 v[146:147], v[68:69], v[186:187], v[68:69] op_sel_hi:[1,0,1] neg_lo:[1,0,0] neg_hi:[1,0,0]
	v_pk_fma_f32 v[78:79], v[70:71], v[162:163], v[78:79] op_sel:[0,1,0]
	v_pk_fma_f32 v[150:151], v[70:71], v[194:195], v[150:151] op_sel:[0,1,0]
	v_pk_fma_f32 v[148:149], v[70:71], v[186:187], v[70:71] op_sel:[0,1,0] neg_lo:[1,0,0] neg_hi:[1,0,0]
	v_pk_fma_f32 v[142:143], v[242:243], v[188:189], v[142:143] op_sel_hi:[1,0,1]
	v_pk_fma_f32 v[144:145], v[242:243], v[188:189], v[144:145] op_sel:[0,1,0]
	v_add_f32_dpp v150, v150, v150 quad_perm:[1,0,3,2] row_mask:0xf bank_mask:0xf bound_ctrl:1
	v_add_f32_dpp v151, v151, v151 quad_perm:[1,0,3,2] row_mask:0xf bank_mask:0xf bound_ctrl:1
	v_pk_fma_f32 v[146:147], v[242:243], v[190:191], v[146:147] op_sel_hi:[1,0,1]
	v_add_f32_dpp v150, v150, v150 quad_perm:[2,3,0,1] row_mask:0xf bank_mask:0xf bound_ctrl:1
	v_add_f32_dpp v151, v151, v151 quad_perm:[2,3,0,1] row_mask:0xf bank_mask:0xf bound_ctrl:1
	v_pk_fma_f32 v[148:149], v[242:243], v[190:191], v[148:149] op_sel:[0,1,0]
	v_add_f32_dpp v150, v150, v150 row_half_mirror row_mask:0xf bank_mask:0xf bound_ctrl:1
	v_add_f32_dpp v151, v151, v151 row_half_mirror row_mask:0xf bank_mask:0xf bound_ctrl:1
	s_nop 0
	s_waitcnt lgkmcnt(0)
; #define LAS __attribute__((address_space(3)))
; #define ROW16_SUM4(x, y, z, w) do { DPP4(x, y, z, w, "quad_perm:[1,0,3,2]", "s_nop 1"); DPP4(x, y, z, w, "quad_perm:[2,3,0,1]", ""); DPP4(x, y, z, w, "row_half_mirror", ""); DPP4(x, y, z, w, "row_mirror", ""); } while (0)
; template <bool SAMPLE>
; __device__ __forceinline__ void rwkv_unit(PR P, LAS float* lds, const int b, const int h, const int half, const int wv) {
;     ...
;                 for (int tt = 0; tt < GS; ++tt) {
;                     const LAS float* qn = q0 + (tt + 1 < GS ? tt + 1 : tt) * 384;
;                     const f32x4 nr4 = *(const LAS f32x4*)(qn + j0), no4 = *(const LAS f32x4*)(qn + 64 + j0), nk4 = *(const LAS f32x4*)(qn + 128 + j0), na4 = *(const LAS f32x4*)(qn + 192 + j0), nb4 = *(const LAS f32x4*)(qn + 256 + j0);
;                     const f32x2 nv2 = *(const LAS f32x2*)(qn + 320 + row0);
;                     f32x2 sa = (S[0] * a4[0] + S[1] * a4[1]) + (S[2] * a4[2] + S[3] * a4[3]);
;                     float sx = sa.x, sy = sa.y; ROW16_SUM4(sx, sy, py0, py1); sa = (f32x2){sx, sy};
;                     if (tt > 0) { yk0 = cgl == tt - 1 ? py0 : yk0; yk1 = cgl == tt - 1 ? py1 : yk1; }
; #pragma unroll
;                     for (int c = 0; c < 4; ++c) { f32x2 t = S[c] - S[c] * o4[c]; t = t + sa * b4[c]; S[c] = t + v2 * k4[c]; }
;                     const f32x2 y = (S[0] * r4[0] + S[1] * r4[1]) + (S[2] * r4[2] + S[3] * r4[3]);
;                     py0 = y.x; py1 = y.y;
;                     r4 = nr4; o4 = no4; k4 = nk4; a4 = na4; b4 = nb4; v2 = nv2;
	v_add_f32_dpp v150, v150, v150 row_mirror row_mask:0xf bank_mask:0xf bound_ctrl:1
	v_add_f32_dpp v151, v151, v151 row_mirror row_mask:0xf bank_mask:0xf bound_ctrl:1
	v_pk_fma_f32 v[66:67], v[150:151], v[196:197], v[142:143] op_sel_hi:[1,0,1]
	v_pk_fma_f32 v[20:21], v[150:151], v[196:197], v[144:145] op_sel:[0,1,0]
	v_pk_fma_f32 v[68:69], v[150:151], v[198:199], v[146:147] op_sel_hi:[1,0,1]
	v_pk_fma_f32 v[70:71], v[150:151], v[198:199], v[148:149] op_sel:[0,1,0]
	v_pk_mul_f32 v[80:81], v[66:67], v[180:181] op_sel_hi:[1,0]
	v_pk_mul_f32 v[150:151], v[66:67], v[212:213] op_sel_hi:[1,0]
	v_pk_fma_f32 v[142:143], v[66:67], v[204:205], v[66:67] op_sel_hi:[1,0,1] neg_lo:[1,0,0] neg_hi:[1,0,0]
	ds_read_b128 v[172:175], v152 offset:6912
	v_pk_fma_f32 v[80:81], v[20:21], v[180:181], v[80:81] op_sel:[0,1,0]
	v_pk_fma_f32 v[150:151], v[20:21], v[212:213], v[150:151] op_sel:[0,1,0]
	v_pk_fma_f32 v[144:145], v[20:21], v[204:205], v[20:21] op_sel:[0,1,0] neg_lo:[1,0,0] neg_hi:[1,0,0]
	ds_read_b128 v[164:167], v152 offset:6400
	v_pk_fma_f32 v[80:81], v[68:69], v[182:183], v[80:81] op_sel_hi:[1,0,1]
	v_pk_fma_f32 v[150:151], v[68:69], v[214:215], v[150:151] op_sel_hi:[1,0,1]
	v_pk_fma_f32 v[146:147], v[68:69], v[206:207], v[68:69] op_sel_hi:[1,0,1] neg_lo:[1,0,0] neg_hi:[1,0,0]
	ds_read2st64_b64 v[248:251], v153 offset0:14 offset1:17
	v_pk_fma_f32 v[80:81], v[70:71], v[182:183], v[80:81] op_sel:[0,1,0]
	v_pk_fma_f32 v[150:151], v[70:71], v[214:215], v[150:151] op_sel:[0,1,0]
	v_pk_fma_f32 v[148:149], v[70:71], v[206:207], v[70:71] op_sel:[0,1,0] neg_lo:[1,0,0] neg_hi:[1,0,0]
	ds_read_b128 v[168:171], v152 offset:6656
	v_pk_fma_f32 v[142:143], v[244:245], v[208:209], v[142:143] op_sel_hi:[1,0,1]
	v_pk_fma_f32 v[144:145], v[244:245], v[208:209], v[144:145] op_sel:[0,1,0]
	v_add_f32_dpp v150, v150, v150 quad_perm:[1,0,3,2] row_mask:0xf bank_mask:0xf bound_ctrl:1
	v_add_f32_dpp v151, v151, v151 quad_perm:[1,0,3,2] row_mask:0xf bank_mask:0xf bound_ctrl:1
	v_pk_fma_f32 v[146:147], v[244:245], v[210:211], v[146:147] op_sel_hi:[1,0,1]
	v_add_f32_dpp v150, v150, v150 quad_perm:[2,3,0,1] row_mask:0xf bank_mask:0xf bound_ctrl:1
	v_add_f32_dpp v151, v151, v151 quad_perm:[2,3,0,1] row_mask:0xf bank_mask:0xf bound_ctrl:1
	v_pk_fma_f32 v[148:149], v[244:245], v[210:211], v[148:149] op_sel:[0,1,0]
	v_add_f32_dpp v150, v150, v150 row_half_mirror row_mask:0xf bank_mask:0xf bound_ctrl:1
	v_add_f32_dpp v151, v151, v151 row_half_mirror row_mask:0xf bank_mask:0xf bound_ctrl:1
	ds_read_b128 v[192:195], v152 offset:8448
	v_add_f32_dpp v150, v150, v150 row_mirror row_mask:0xf bank_mask:0xf bound_ctrl:1
	v_add_f32_dpp v151, v151, v151 row_mirror row_mask:0xf bank_mask:0xf bound_ctrl:1
	ds_read_b128 v[184:187], v152 offset:7936
	ds_read_b128 v[176:179], v152 offset:7168
	ds_read_b128 v[188:191], v152 offset:8192
	ds_read_b128 v[196:199], v152 offset:8704
	ds_read_b128 v[160:163], v152 offset:6144
	ds_read_b128 v[180:183], v152 offset:7680
	v_pk_fma_f32 v[66:67], v[150:151], v[216:217], v[142:143] op_sel_hi:[1,0,1]
	v_pk_fma_f32 v[20:21], v[150:151], v[216:217], v[144:145] op_sel:[0,1,0]
	v_pk_fma_f32 v[68:69], v[150:151], v[218:219], v[146:147] op_sel_hi:[1,0,1]
	v_pk_fma_f32 v[70:71], v[150:151], v[218:219], v[148:149] op_sel:[0,1,0]
	v_pk_mul_f32 v[82:83], v[66:67], v[200:201] op_sel_hi:[1,0]
	v_pk_mul_f32 v[150:151], v[66:67], v[232:233] op_sel_hi:[1,0]
	v_pk_fma_f32 v[142:143], v[66:67], v[224:225], v[66:67] op_sel_hi:[1,0,1] neg_lo:[1,0,0] neg_hi:[1,0,0]
	v_pk_fma_f32 v[82:83], v[20:21], v[200:201], v[82:83] op_sel:[0,1,0]
	v_pk_fma_f32 v[150:151], v[20:21], v[232:233], v[150:151] op_sel:[0,1,0]
	v_pk_fma_f32 v[144:145], v[20:21], v[224:225], v[20:21] op_sel:[0,1,0] neg_lo:[1,0,0] neg_hi:[1,0,0]
	v_pk_fma_f32 v[82:83], v[68:69], v[202:203], v[82:83] op_sel_hi:[1,0,1]
	v_pk_fma_f32 v[150:151], v[68:69], v[234:235], v[150:151] op_sel_hi:[1,0,1]
	v_pk_fma_f32 v[146:147], v[68:69], v[226:227], v[68:69] op_sel_hi:[1,0,1] neg_lo:[1,0,0] neg_hi:[1,0,0]
	v_pk_fma_f32 v[82:83], v[70:71], v[202:203], v[82:83] op_sel:[0,1,0]
	v_pk_fma_f32 v[150:151], v[70:71], v[234:235], v[150:151] op_sel:[0,1,0]
	v_pk_fma_f32 v[148:149], v[70:71], v[226:227], v[70:71] op_sel:[0,1,0] neg_lo:[1,0,0] neg_hi:[1,0,0]
	v_pk_fma_f32 v[142:143], v[246:247], v[228:229], v[142:143] op_sel_hi:[1,0,1]
	v_pk_fma_f32 v[144:145], v[246:247], v[228:229], v[144:145] op_sel:[0,1,0]
	v_add_f32_dpp v150, v150, v150 quad_perm:[1,0,3,2] row_mask:0xf bank_mask:0xf bound_ctrl:1
	v_add_f32_dpp v151, v151, v151 quad_perm:[1,0,3,2] row_mask:0xf bank_mask:0xf bound_ctrl:1
	v_pk_fma_f32 v[146:147], v[246:247], v[230:231], v[146:147] op_sel_hi:[1,0,1]
	v_add_f32_dpp v150, v150, v150 quad_perm:[2,3,0,1] row_mask:0xf bank_mask:0xf bound_ctrl:1
	v_add_f32_dpp v151, v151, v151 quad_perm:[2,3,0,1] row_mask:0xf bank_mask:0xf bound_ctrl:1
	v_pk_fma_f32 v[148:149], v[246:247], v[230:231], v[148:149] op_sel:[0,1,0]
	v_add_f32_dpp v150, v150, v150 row_half_mirror row_mask:0xf bank_mask:0xf bound_ctrl:1
	v_add_f32_dpp v151, v151, v151 row_half_mirror row_mask:0xf bank_mask:0xf bound_ctrl:1
	s_nop 0
	s_waitcnt lgkmcnt(0)
; #define LAS __attribute__((address_space(3)))
; #define ROW16_SUM4(x, y, z, w) do { DPP4(x, y, z, w, "quad_perm:[1,0,3,2]", "s_nop 1"); DPP4(x, y, z, w, "quad_perm:[2,3,0,1]", ""); DPP4(x, y, z, w, "row_half_mirror", ""); DPP4(x, y, z, w, "row_mirror", ""); } while (0)
; template <bool SAMPLE>
; __device__ __forceinline__ void rwkv_unit(PR P, LAS float* lds, const int b, const int h, const int half, const int wv) {
;     ...
;                 for (int tt = 0; tt < GS; ++tt) {
;                     const LAS float* qn = q0 + (tt + 1 < GS ? tt + 1 : tt) * 384;
;                     const f32x4 nr4 = *(const LAS f32x4*)(qn + j0), no4 = *(const LAS f32x4*)(qn + 64 + j0), nk4 = *(const LAS f32x4*)(qn + 128 + j0), na4 = *(const LAS f32x4*)(qn + 192 + j0), nb4 = *(const LAS f32x4*)(qn + 256 + j0);
;                     const f32x2 nv2 = *(const LAS f32x2*)(qn + 320 + row0);
;                     f32x2 sa = (S[0] * a4[0] + S[1] * a4[1]) + (S[2] * a4[2] + S[3] * a4[3]);
;                     float sx = sa.x, sy = sa.y; ROW16_SUM4(sx, sy, py0, py1); sa = (f32x2){sx, sy};
;                     if (tt > 0) { yk0 = cgl == tt - 1 ? py0 : yk0; yk1 = cgl == tt - 1 ? py1 : yk1; }
; #pragma unroll
;                     for (int c = 0; c < 4; ++c) { f32x2 t = S[c] - S[c] * o4[c]; t = t + sa * b4[c]; S[c] = t + v2 * k4[c]; }
;                     const f32x2 y = (S[0] * r4[0] + S[1] * r4[1]) + (S[2] * r4[2] + S[3] * r4[3]);
;                     py0 = y.x; py1 = y.y;
;                     r4 = nr4; o4 = no4; k4 = nk4; a4 = na4; b4 = nb4; v2 = nv2;
	v_add_f32_dpp v150, v150, v150 row_mirror row_mask:0xf bank_mask:0xf bound_ctrl:1
	v_add_f32_dpp v151, v151, v151 row_mirror row_mask:0xf bank_mask:0xf bound_ctrl:1
	v_pk_fma_f32 v[66:67], v[150:151], v[236:237], v[142:143] op_sel_hi:[1,0,1]
	v_pk_fma_f32 v[20:21], v[150:151], v[236:237], v[144:145] op_sel:[0,1,0]
	v_pk_fma_f32 v[68:69], v[150:151], v[238:239], v[146:147] op_sel_hi:[1,0,1]
	v_pk_fma_f32 v[70:71], v[150:151], v[238:239], v[148:149] op_sel:[0,1,0]
	v_pk_mul_f32 v[84:85], v[66:67], v[220:221] op_sel_hi:[1,0]
	v_pk_mul_f32 v[150:151], v[66:67], v[172:173] op_sel_hi:[1,0]
	v_pk_fma_f32 v[142:143], v[66:67], v[164:165], v[66:67] op_sel_hi:[1,0,1] neg_lo:[1,0,0] neg_hi:[1,0,0]
	ds_read_b128 v[212:215], v152 offset:9984
	v_pk_fma_f32 v[84:85], v[20:21], v[220:221], v[84:85] op_sel:[0,1,0]
	v_pk_fma_f32 v[150:151], v[20:21], v[172:173], v[150:151] op_sel:[0,1,0]
	v_pk_fma_f32 v[144:145], v[20:21], v[164:165], v[20:21] op_sel:[0,1,0] neg_lo:[1,0,0] neg_hi:[1,0,0]
	ds_read_b128 v[204:207], v152 offset:9472
	v_pk_fma_f32 v[84:85], v[68:69], v[222:223], v[84:85] op_sel_hi:[1,0,1]
	v_pk_fma_f32 v[150:151], v[68:69], v[174:175], v[150:151] op_sel_hi:[1,0,1]
	v_pk_fma_f32 v[146:147], v[68:69], v[166:167], v[68:69] op_sel_hi:[1,0,1] neg_lo:[1,0,0] neg_hi:[1,0,0]
	ds_read2st64_b64 v[240:243], v153 offset0:20 offset1:23
	v_pk_fma_f32 v[84:85], v[70:71], v[222:223], v[84:85] op_sel:[0,1,0]
	v_pk_fma_f32 v[150:151], v[70:71], v[174:175], v[150:151] op_sel:[0,1,0]
	v_pk_fma_f32 v[148:149], v[70:71], v[166:167], v[70:71] op_sel:[0,1,0] neg_lo:[1,0,0] neg_hi:[1,0,0]
	ds_read_b128 v[208:211], v152 offset:9728
	v_pk_fma_f32 v[142:143], v[248:249], v[168:169], v[142:143] op_sel_hi:[1,0,1]
	v_pk_fma_f32 v[144:145], v[248:249], v[168:169], v[144:145] op_sel:[0,1,0]
	v_add_f32_dpp v150, v150, v150 quad_perm:[1,0,3,2] row_mask:0xf bank_mask:0xf bound_ctrl:1
	v_add_f32_dpp v151, v151, v151 quad_perm:[1,0,3,2] row_mask:0xf bank_mask:0xf bound_ctrl:1
	v_pk_fma_f32 v[146:147], v[248:249], v[170:171], v[146:147] op_sel_hi:[1,0,1]
	v_add_f32_dpp v150, v150, v150 quad_perm:[2,3,0,1] row_mask:0xf bank_mask:0xf bound_ctrl:1
	v_add_f32_dpp v151, v151, v151 quad_perm:[2,3,0,1] row_mask:0xf bank_mask:0xf bound_ctrl:1
	v_pk_fma_f32 v[148:149], v[248:249], v[170:171], v[148:149] op_sel:[0,1,0]
	v_add_f32_dpp v150, v150, v150 row_half_mirror row_mask:0xf bank_mask:0xf bound_ctrl:1
	v_add_f32_dpp v151, v151, v151 row_half_mirror row_mask:0xf bank_mask:0xf bound_ctrl:1
	ds_read_b128 v[232:235], v152 offset:11520
	v_add_f32_dpp v150, v150, v150 row_mirror row_mask:0xf bank_mask:0xf bound_ctrl:1
	v_add_f32_dpp v151, v151, v151 row_mirror row_mask:0xf bank_mask:0xf bound_ctrl:1
	ds_read_b128 v[224:227], v152 offset:11008
	ds_read_b128 v[216:219], v152 offset:10240
	ds_read_b128 v[228:231], v152 offset:11264
	ds_read_b128 v[236:239], v152 offset:11776
	ds_read_b128 v[200:203], v152 offset:9216
	ds_read_b128 v[220:223], v152 offset:10752
	v_pk_fma_f32 v[66:67], v[150:151], v[176:177], v[142:143] op_sel_hi:[1,0,1]
	v_pk_fma_f32 v[20:21], v[150:151], v[176:177], v[144:145] op_sel:[0,1,0]
	v_pk_fma_f32 v[68:69], v[150:151], v[178:179], v[146:147] op_sel_hi:[1,0,1]
	v_pk_fma_f32 v[70:71], v[150:151], v[178:179], v[148:149] op_sel:[0,1,0]
	v_pk_mul_f32 v[86:87], v[66:67], v[160:161] op_sel_hi:[1,0]
	v_pk_mul_f32 v[150:151], v[66:67], v[192:193] op_sel_hi:[1,0]
	v_pk_fma_f32 v[142:143], v[66:67], v[184:185], v[66:67] op_sel_hi:[1,0,1] neg_lo:[1,0,0] neg_hi:[1,0,0]
	v_pk_fma_f32 v[86:87], v[20:21], v[160:161], v[86:87] op_sel:[0,1,0]
	v_pk_fma_f32 v[150:151], v[20:21], v[192:193], v[150:151] op_sel:[0,1,0]
	v_pk_fma_f32 v[144:145], v[20:21], v[184:185], v[20:21] op_sel:[0,1,0] neg_lo:[1,0,0] neg_hi:[1,0,0]
	v_pk_fma_f32 v[86:87], v[68:69], v[162:163], v[86:87] op_sel_hi:[1,0,1]
	v_pk_fma_f32 v[150:151], v[68:69], v[194:195], v[150:151] op_sel_hi:[1,0,1]
	v_pk_fma_f32 v[146:147], v[68:69], v[186:187], v[68:69] op_sel_hi:[1,0,1] neg_lo:[1,0,0] neg_hi:[1,0,0]
	v_pk_fma_f32 v[86:87], v[70:71], v[162:163], v[86:87] op_sel:[0,1,0]
	v_pk_fma_f32 v[150:151], v[70:71], v[194:195], v[150:151] op_sel:[0,1,0]
	v_pk_fma_f32 v[148:149], v[70:71], v[186:187], v[70:71] op_sel:[0,1,0] neg_lo:[1,0,0] neg_hi:[1,0,0]
	v_pk_fma_f32 v[142:143], v[250:251], v[188:189], v[142:143] op_sel_hi:[1,0,1]
	v_pk_fma_f32 v[144:145], v[250:251], v[188:189], v[144:145] op_sel:[0,1,0]
	v_add_f32_dpp v150, v150, v150 quad_perm:[1,0,3,2] row_mask:0xf bank_mask:0xf bound_ctrl:1
	v_add_f32_dpp v151, v151, v151 quad_perm:[1,0,3,2] row_mask:0xf bank_mask:0xf bound_ctrl:1
	v_pk_fma_f32 v[146:147], v[250:251], v[190:191], v[146:147] op_sel_hi:[1,0,1]
	v_add_f32_dpp v150, v150, v150 quad_perm:[2,3,0,1] row_mask:0xf bank_mask:0xf bound_ctrl:1
	v_add_f32_dpp v151, v151, v151 quad_perm:[2,3,0,1] row_mask:0xf bank_mask:0xf bound_ctrl:1
	v_pk_fma_f32 v[148:149], v[250:251], v[190:191], v[148:149] op_sel:[0,1,0]
	v_add_f32_dpp v150, v150, v150 row_half_mirror row_mask:0xf bank_mask:0xf bound_ctrl:1
	v_add_f32_dpp v151, v151, v151 row_half_mirror row_mask:0xf bank_mask:0xf bound_ctrl:1
	s_nop 0
	s_waitcnt lgkmcnt(0)
; #define LAS __attribute__((address_space(3)))
; #define ROW16_SUM4(x, y, z, w) do { DPP4(x, y, z, w, "quad_perm:[1,0,3,2]", "s_nop 1"); DPP4(x, y, z, w, "quad_perm:[2,3,0,1]", ""); DPP4(x, y, z, w, "row_half_mirror", ""); DPP4(x, y, z, w, "row_mirror", ""); } while (0)
; template <bool SAMPLE>
; __device__ __forceinline__ void rwkv_unit(PR P, LAS float* lds, const int b, const int h, const int half, const int wv) {
;     ...
;                 for (int tt = 0; tt < GS; ++tt) {
;                     const LAS float* qn = q0 + (tt + 1 < GS ? tt + 1 : tt) * 384;
;                     const f32x4 nr4 = *(const LAS f32x4*)(qn + j0), no4 = *(const LAS f32x4*)(qn + 64 + j0), nk4 = *(const LAS f32x4*)(qn + 128 + j0), na4 = *(const LAS f32x4*)(qn + 192 + j0), nb4 = *(const LAS f32x4*)(qn + 256 + j0);
;                     const f32x2 nv2 = *(const LAS f32x2*)(qn + 320 + row0);
;                     f32x2 sa = (S[0] * a4[0] + S[1] * a4[1]) + (S[2] * a4[2] + S[3] * a4[3]);
;                     float sx = sa.x, sy = sa.y; ROW16_SUM4(sx, sy, py0, py1); sa = (f32x2){sx, sy};
;                     if (tt > 0) { yk0 = cgl == tt - 1 ? py0 : yk0; yk1 = cgl == tt - 1 ? py1 : yk1; }
; #pragma unroll
;                     for (int c = 0; c < 4; ++c) { f32x2 t = S[c] - S[c] * o4[c]; t = t + sa * b4[c]; S[c] = t + v2 * k4[c]; }
;                     const f32x2 y = (S[0] * r4[0] + S[1] * r4[1]) + (S[2] * r4[2] + S[3] * r4[3]);
;                     py0 = y.x; py1 = y.y;
;                     r4 = nr4; o4 = no4; k4 = nk4; a4 = na4; b4 = nb4; v2 = nv2;
	v_add_f32_dpp v150, v150, v150 row_mirror row_mask:0xf bank_mask:0xf bound_ctrl:1
	v_add_f32_dpp v151, v151, v151 row_mirror row_mask:0xf bank_mask:0xf bound_ctrl:1
	v_pk_fma_f32 v[66:67], v[150:151], v[196:197], v[142:143] op_sel_hi:[1,0,1]
	v_pk_fma_f32 v[20:21], v[150:151], v[196:197], v[144:145] op_sel:[0,1,0]
	v_pk_fma_f32 v[68:69], v[150:151], v[198:199], v[146:147] op_sel_hi:[1,0,1]
	v_pk_fma_f32 v[70:71], v[150:151], v[198:199], v[148:149] op_sel:[0,1,0]
	v_pk_mul_f32 v[88:89], v[66:67], v[180:181] op_sel_hi:[1,0]
	v_pk_mul_f32 v[150:151], v[66:67], v[212:213] op_sel_hi:[1,0]
	v_pk_fma_f32 v[142:143], v[66:67], v[204:205], v[66:67] op_sel_hi:[1,0,1] neg_lo:[1,0,0] neg_hi:[1,0,0]
	ds_read_b128 v[172:175], v152 offset:13056
	v_pk_fma_f32 v[88:89], v[20:21], v[180:181], v[88:89] op_sel:[0,1,0]
	v_pk_fma_f32 v[150:151], v[20:21], v[212:213], v[150:151] op_sel:[0,1,0]
	v_pk_fma_f32 v[144:145], v[20:21], v[204:205], v[20:21] op_sel:[0,1,0] neg_lo:[1,0,0] neg_hi:[1,0,0]
	ds_read_b128 v[164:167], v152 offset:12544
	v_pk_fma_f32 v[88:89], v[68:69], v[182:183], v[88:89] op_sel_hi:[1,0,1]
	v_pk_fma_f32 v[150:151], v[68:69], v[214:215], v[150:151] op_sel_hi:[1,0,1]
	v_pk_fma_f32 v[146:147], v[68:69], v[206:207], v[68:69] op_sel_hi:[1,0,1] neg_lo:[1,0,0] neg_hi:[1,0,0]
	ds_read2st64_b64 v[244:247], v153 offset0:26 offset1:29
	v_pk_fma_f32 v[88:89], v[70:71], v[182:183], v[88:89] op_sel:[0,1,0]
	v_pk_fma_f32 v[150:151], v[70:71], v[214:215], v[150:151] op_sel:[0,1,0]
	v_pk_fma_f32 v[148:149], v[70:71], v[206:207], v[70:71] op_sel:[0,1,0] neg_lo:[1,0,0] neg_hi:[1,0,0]
	ds_read_b128 v[168:171], v152 offset:12800
	v_pk_fma_f32 v[142:143], v[240:241], v[208:209], v[142:143] op_sel_hi:[1,0,1]
	v_pk_fma_f32 v[144:145], v[240:241], v[208:209], v[144:145] op_sel:[0,1,0]
	v_add_f32_dpp v150, v150, v150 quad_perm:[1,0,3,2] row_mask:0xf bank_mask:0xf bound_ctrl:1
	v_add_f32_dpp v151, v151, v151 quad_perm:[1,0,3,2] row_mask:0xf bank_mask:0xf bound_ctrl:1
	v_pk_fma_f32 v[146:147], v[240:241], v[210:211], v[146:147] op_sel_hi:[1,0,1]
	v_add_f32_dpp v150, v150, v150 quad_perm:[2,3,0,1] row_mask:0xf bank_mask:0xf bound_ctrl:1
	v_add_f32_dpp v151, v151, v151 quad_perm:[2,3,0,1] row_mask:0xf bank_mask:0xf bound_ctrl:1
	v_pk_fma_f32 v[148:149], v[240:241], v[210:211], v[148:149] op_sel:[0,1,0]
	v_add_f32_dpp v150, v150, v150 row_half_mirror row_mask:0xf bank_mask:0xf bound_ctrl:1
	v_add_f32_dpp v151, v151, v151 row_half_mirror row_mask:0xf bank_mask:0xf bound_ctrl:1
	ds_read_b128 v[192:195], v152 offset:14592
	v_add_f32_dpp v150, v150, v150 row_mirror row_mask:0xf bank_mask:0xf bound_ctrl:1
	v_add_f32_dpp v151, v151, v151 row_mirror row_mask:0xf bank_mask:0xf bound_ctrl:1
	ds_read_b128 v[184:187], v152 offset:14080
	ds_read_b128 v[176:179], v152 offset:13312
	ds_read_b128 v[188:191], v152 offset:14336
	ds_read_b128 v[196:199], v152 offset:14848
	ds_read_b128 v[160:163], v152 offset:12288
	ds_read_b128 v[180:183], v152 offset:13824
	v_pk_fma_f32 v[66:67], v[150:151], v[216:217], v[142:143] op_sel_hi:[1,0,1]
	v_pk_fma_f32 v[20:21], v[150:151], v[216:217], v[144:145] op_sel:[0,1,0]
	v_pk_fma_f32 v[68:69], v[150:151], v[218:219], v[146:147] op_sel_hi:[1,0,1]
	v_pk_fma_f32 v[70:71], v[150:151], v[218:219], v[148:149] op_sel:[0,1,0]
	v_pk_mul_f32 v[90:91], v[66:67], v[200:201] op_sel_hi:[1,0]
	v_pk_mul_f32 v[150:151], v[66:67], v[232:233] op_sel_hi:[1,0]
	v_pk_fma_f32 v[142:143], v[66:67], v[224:225], v[66:67] op_sel_hi:[1,0,1] neg_lo:[1,0,0] neg_hi:[1,0,0]
	v_pk_fma_f32 v[90:91], v[20:21], v[200:201], v[90:91] op_sel:[0,1,0]
	v_pk_fma_f32 v[150:151], v[20:21], v[232:233], v[150:151] op_sel:[0,1,0]
	v_pk_fma_f32 v[144:145], v[20:21], v[224:225], v[20:21] op_sel:[0,1,0] neg_lo:[1,0,0] neg_hi:[1,0,0]
	v_pk_fma_f32 v[90:91], v[68:69], v[202:203], v[90:91] op_sel_hi:[1,0,1]
	v_pk_fma_f32 v[150:151], v[68:69], v[234:235], v[150:151] op_sel_hi:[1,0,1]
	v_pk_fma_f32 v[146:147], v[68:69], v[226:227], v[68:69] op_sel_hi:[1,0,1] neg_lo:[1,0,0] neg_hi:[1,0,0]
	v_pk_fma_f32 v[90:91], v[70:71], v[202:203], v[90:91] op_sel:[0,1,0]
	v_pk_fma_f32 v[150:151], v[70:71], v[234:235], v[150:151] op_sel:[0,1,0]
	v_pk_fma_f32 v[148:149], v[70:71], v[226:227], v[70:71] op_sel:[0,1,0] neg_lo:[1,0,0] neg_hi:[1,0,0]
	v_pk_fma_f32 v[142:143], v[242:243], v[228:229], v[142:143] op_sel_hi:[1,0,1]
	v_pk_fma_f32 v[144:145], v[242:243], v[228:229], v[144:145] op_sel:[0,1,0]
	v_add_f32_dpp v150, v150, v150 quad_perm:[1,0,3,2] row_mask:0xf bank_mask:0xf bound_ctrl:1
	v_add_f32_dpp v151, v151, v151 quad_perm:[1,0,3,2] row_mask:0xf bank_mask:0xf bound_ctrl:1
	v_pk_fma_f32 v[146:147], v[242:243], v[230:231], v[146:147] op_sel_hi:[1,0,1]
	v_add_f32_dpp v150, v150, v150 quad_perm:[2,3,0,1] row_mask:0xf bank_mask:0xf bound_ctrl:1
	v_add_f32_dpp v151, v151, v151 quad_perm:[2,3,0,1] row_mask:0xf bank_mask:0xf bound_ctrl:1
	v_pk_fma_f32 v[148:149], v[242:243], v[230:231], v[148:149] op_sel:[0,1,0]
	v_add_f32_dpp v150, v150, v150 row_half_mirror row_mask:0xf bank_mask:0xf bound_ctrl:1
	v_add_f32_dpp v151, v151, v151 row_half_mirror row_mask:0xf bank_mask:0xf bound_ctrl:1
	s_nop 0
	s_waitcnt lgkmcnt(0)
; #define LAS __attribute__((address_space(3)))
; #define ROW16_SUM4(x, y, z, w) do { DPP4(x, y, z, w, "quad_perm:[1,0,3,2]", "s_nop 1"); DPP4(x, y, z, w, "quad_perm:[2,3,0,1]", ""); DPP4(x, y, z, w, "row_half_mirror", ""); DPP4(x, y, z, w, "row_mirror", ""); } while (0)
; template <bool SAMPLE>
; __device__ __forceinline__ void rwkv_unit(PR P, LAS float* lds, const int b, const int h, const int half, const int wv) {
;     ...
;                 for (int tt = 0; tt < GS; ++tt) {
;                     const LAS float* qn = q0 + (tt + 1 < GS ? tt + 1 : tt) * 384;
;                     const f32x4 nr4 = *(const LAS f32x4*)(qn + j0), no4 = *(const LAS f32x4*)(qn + 64 + j0), nk4 = *(const LAS f32x4*)(qn + 128 + j0), na4 = *(const LAS f32x4*)(qn + 192 + j0), nb4 = *(const LAS f32x4*)(qn + 256 + j0);
;                     const f32x2 nv2 = *(const LAS f32x2*)(qn + 320 + row0);
;                     f32x2 sa = (S[0] * a4[0] + S[1] * a4[1]) + (S[2] * a4[2] + S[3] * a4[3]);
;                     float sx = sa.x, sy = sa.y; ROW16_SUM4(sx, sy, py0, py1); sa = (f32x2){sx, sy};
;                     if (tt > 0) { yk0 = cgl == tt - 1 ? py0 : yk0; yk1 = cgl == tt - 1 ? py1 : yk1; }
; #pragma unroll
;                     for (int c = 0; c < 4; ++c) { f32x2 t = S[c] - S[c] * o4[c]; t = t + sa * b4[c]; S[c] = t + v2 * k4[c]; }
;                     const f32x2 y = (S[0] * r4[0] + S[1] * r4[1]) + (S[2] * r4[2] + S[3] * r4[3]);
;                     py0 = y.x; py1 = y.y;
;                     r4 = nr4; o4 = no4; k4 = nk4; a4 = na4; b4 = nb4; v2 = nv2;
	v_add_f32_dpp v150, v150, v150 row_mirror row_mask:0xf bank_mask:0xf bound_ctrl:1
	v_add_f32_dpp v151, v151, v151 row_mirror row_mask:0xf bank_mask:0xf bound_ctrl:1
	v_pk_fma_f32 v[66:67], v[150:151], v[236:237], v[142:143] op_sel_hi:[1,0,1]
	v_pk_fma_f32 v[20:21], v[150:151], v[236:237], v[144:145] op_sel:[0,1,0]
	v_pk_fma_f32 v[68:69], v[150:151], v[238:239], v[146:147] op_sel_hi:[1,0,1]
	v_pk_fma_f32 v[70:71], v[150:151], v[238:239], v[148:149] op_sel:[0,1,0]
	v_pk_mul_f32 v[92:93], v[66:67], v[220:221] op_sel_hi:[1,0]
	v_pk_mul_f32 v[150:151], v[66:67], v[172:173] op_sel_hi:[1,0]
	v_pk_fma_f32 v[142:143], v[66:67], v[164:165], v[66:67] op_sel_hi:[1,0,1] neg_lo:[1,0,0] neg_hi:[1,0,0]
	ds_read_b128 v[212:215], v152 offset:16128
	v_pk_fma_f32 v[92:93], v[20:21], v[220:221], v[92:93] op_sel:[0,1,0]
	v_pk_fma_f32 v[150:151], v[20:21], v[172:173], v[150:151] op_sel:[0,1,0]
	v_pk_fma_f32 v[144:145], v[20:21], v[164:165], v[20:21] op_sel:[0,1,0] neg_lo:[1,0,0] neg_hi:[1,0,0]
	ds_read_b128 v[204:207], v152 offset:15616
	v_pk_fma_f32 v[92:93], v[68:69], v[222:223], v[92:93] op_sel_hi:[1,0,1]
	v_pk_fma_f32 v[150:151], v[68:69], v[174:175], v[150:151] op_sel_hi:[1,0,1]
	v_pk_fma_f32 v[146:147], v[68:69], v[166:167], v[68:69] op_sel_hi:[1,0,1] neg_lo:[1,0,0] neg_hi:[1,0,0]
	ds_read2st64_b64 v[248:251], v153 offset0:32 offset1:35
	v_pk_fma_f32 v[92:93], v[70:71], v[222:223], v[92:93] op_sel:[0,1,0]
	v_pk_fma_f32 v[150:151], v[70:71], v[174:175], v[150:151] op_sel:[0,1,0]
	v_pk_fma_f32 v[148:149], v[70:71], v[166:167], v[70:71] op_sel:[0,1,0] neg_lo:[1,0,0] neg_hi:[1,0,0]
	ds_read_b128 v[208:211], v152 offset:15872
	v_pk_fma_f32 v[142:143], v[244:245], v[168:169], v[142:143] op_sel_hi:[1,0,1]
	v_pk_fma_f32 v[144:145], v[244:245], v[168:169], v[144:145] op_sel:[0,1,0]
	v_add_f32_dpp v150, v150, v150 quad_perm:[1,0,3,2] row_mask:0xf bank_mask:0xf bound_ctrl:1
	v_add_f32_dpp v151, v151, v151 quad_perm:[1,0,3,2] row_mask:0xf bank_mask:0xf bound_ctrl:1
	v_pk_fma_f32 v[146:147], v[244:245], v[170:171], v[146:147] op_sel_hi:[1,0,1]
	v_add_f32_dpp v150, v150, v150 quad_perm:[2,3,0,1] row_mask:0xf bank_mask:0xf bound_ctrl:1
	v_add_f32_dpp v151, v151, v151 quad_perm:[2,3,0,1] row_mask:0xf bank_mask:0xf bound_ctrl:1
	v_pk_fma_f32 v[148:149], v[244:245], v[170:171], v[148:149] op_sel:[0,1,0]
	v_add_f32_dpp v150, v150, v150 row_half_mirror row_mask:0xf bank_mask:0xf bound_ctrl:1
	v_add_f32_dpp v151, v151, v151 row_half_mirror row_mask:0xf bank_mask:0xf bound_ctrl:1
	ds_read_b128 v[232:235], v152 offset:17664
	v_add_f32_dpp v150, v150, v150 row_mirror row_mask:0xf bank_mask:0xf bound_ctrl:1
	v_add_f32_dpp v151, v151, v151 row_mirror row_mask:0xf bank_mask:0xf bound_ctrl:1
	ds_read_b128 v[224:227], v152 offset:17152
	ds_read_b128 v[216:219], v152 offset:16384
	ds_read_b128 v[228:231], v152 offset:17408
	ds_read_b128 v[236:239], v152 offset:17920
	ds_read_b128 v[200:203], v152 offset:15360
	ds_read_b128 v[220:223], v152 offset:16896
	v_pk_fma_f32 v[66:67], v[150:151], v[176:177], v[142:143] op_sel_hi:[1,0,1]
	v_pk_fma_f32 v[20:21], v[150:151], v[176:177], v[144:145] op_sel:[0,1,0]
	v_pk_fma_f32 v[68:69], v[150:151], v[178:179], v[146:147] op_sel_hi:[1,0,1]
	v_pk_fma_f32 v[70:71], v[150:151], v[178:179], v[148:149] op_sel:[0,1,0]
	v_pk_mul_f32 v[94:95], v[66:67], v[160:161] op_sel_hi:[1,0]
	v_pk_mul_f32 v[150:151], v[66:67], v[192:193] op_sel_hi:[1,0]
	v_pk_fma_f32 v[142:143], v[66:67], v[184:185], v[66:67] op_sel_hi:[1,0,1] neg_lo:[1,0,0] neg_hi:[1,0,0]
	v_pk_fma_f32 v[94:95], v[20:21], v[160:161], v[94:95] op_sel:[0,1,0]
	v_pk_fma_f32 v[150:151], v[20:21], v[192:193], v[150:151] op_sel:[0,1,0]
	v_pk_fma_f32 v[144:145], v[20:21], v[184:185], v[20:21] op_sel:[0,1,0] neg_lo:[1,0,0] neg_hi:[1,0,0]
	v_pk_fma_f32 v[94:95], v[68:69], v[162:163], v[94:95] op_sel_hi:[1,0,1]
	v_pk_fma_f32 v[150:151], v[68:69], v[194:195], v[150:151] op_sel_hi:[1,0,1]
	v_pk_fma_f32 v[146:147], v[68:69], v[186:187], v[68:69] op_sel_hi:[1,0,1] neg_lo:[1,0,0] neg_hi:[1,0,0]
	v_pk_fma_f32 v[94:95], v[70:71], v[162:163], v[94:95] op_sel:[0,1,0]
	v_pk_fma_f32 v[150:151], v[70:71], v[194:195], v[150:151] op_sel:[0,1,0]
	v_pk_fma_f32 v[148:149], v[70:71], v[186:187], v[70:71] op_sel:[0,1,0] neg_lo:[1,0,0] neg_hi:[1,0,0]
	v_pk_fma_f32 v[142:143], v[246:247], v[188:189], v[142:143] op_sel_hi:[1,0,1]
	v_pk_fma_f32 v[144:145], v[246:247], v[188:189], v[144:145] op_sel:[0,1,0]
	v_add_f32_dpp v150, v150, v150 quad_perm:[1,0,3,2] row_mask:0xf bank_mask:0xf bound_ctrl:1
	v_add_f32_dpp v151, v151, v151 quad_perm:[1,0,3,2] row_mask:0xf bank_mask:0xf bound_ctrl:1
	v_pk_fma_f32 v[146:147], v[246:247], v[190:191], v[146:147] op_sel_hi:[1,0,1]
	v_add_f32_dpp v150, v150, v150 quad_perm:[2,3,0,1] row_mask:0xf bank_mask:0xf bound_ctrl:1
	v_add_f32_dpp v151, v151, v151 quad_perm:[2,3,0,1] row_mask:0xf bank_mask:0xf bound_ctrl:1
	v_pk_fma_f32 v[148:149], v[246:247], v[190:191], v[148:149] op_sel:[0,1,0]
	v_add_f32_dpp v150, v150, v150 row_half_mirror row_mask:0xf bank_mask:0xf bound_ctrl:1
	v_add_f32_dpp v151, v151, v151 row_half_mirror row_mask:0xf bank_mask:0xf bound_ctrl:1
	s_nop 0
	s_waitcnt lgkmcnt(0)
; #define LAS __attribute__((address_space(3)))
; #define ROW16_SUM4(x, y, z, w) do { DPP4(x, y, z, w, "quad_perm:[1,0,3,2]", "s_nop 1"); DPP4(x, y, z, w, "quad_perm:[2,3,0,1]", ""); DPP4(x, y, z, w, "row_half_mirror", ""); DPP4(x, y, z, w, "row_mirror", ""); } while (0)
; template <bool SAMPLE>
; __device__ __forceinline__ void rwkv_unit(PR P, LAS float* lds, const int b, const int h, const int half, const int wv) {
;     ...
;                 for (int tt = 0; tt < GS; ++tt) {
;                     const LAS float* qn = q0 + (tt + 1 < GS ? tt + 1 : tt) * 384;
;                     const f32x4 nr4 = *(const LAS f32x4*)(qn + j0), no4 = *(const LAS f32x4*)(qn + 64 + j0), nk4 = *(const LAS f32x4*)(qn + 128 + j0), na4 = *(const LAS f32x4*)(qn + 192 + j0), nb4 = *(const LAS f32x4*)(qn + 256 + j0);
;                     const f32x2 nv2 = *(const LAS f32x2*)(qn + 320 + row0);
;                     f32x2 sa = (S[0] * a4[0] + S[1] * a4[1]) + (S[2] * a4[2] + S[3] * a4[3]);
;                     float sx = sa.x, sy = sa.y; ROW16_SUM4(sx, sy, py0, py1); sa = (f32x2){sx, sy};
;                     if (tt > 0) { yk0 = cgl == tt - 1 ? py0 : yk0; yk1 = cgl == tt - 1 ? py1 : yk1; }
; #pragma unroll
;                     for (int c = 0; c < 4; ++c) { f32x2 t = S[c] - S[c] * o4[c]; t = t + sa * b4[c]; S[c] = t + v2 * k4[c]; }
;                     const f32x2 y = (S[0] * r4[0] + S[1] * r4[1]) + (S[2] * r4[2] + S[3] * r4[3]);
;                     py0 = y.x; py1 = y.y;
;                     r4 = nr4; o4 = no4; k4 = nk4; a4 = na4; b4 = nb4; v2 = nv2;
	v_add_f32_dpp v150, v150, v150 row_mirror row_mask:0xf bank_mask:0xf bound_ctrl:1
	v_add_f32_dpp v151, v151, v151 row_mirror row_mask:0xf bank_mask:0xf bound_ctrl:1
	v_pk_fma_f32 v[66:67], v[150:151], v[196:197], v[142:143] op_sel_hi:[1,0,1]
	v_pk_fma_f32 v[20:21], v[150:151], v[196:197], v[144:145] op_sel:[0,1,0]
	v_pk_fma_f32 v[68:69], v[150:151], v[198:199], v[146:147] op_sel_hi:[1,0,1]
	v_pk_fma_f32 v[70:71], v[150:151], v[198:199], v[148:149] op_sel:[0,1,0]
	v_pk_mul_f32 v[96:97], v[66:67], v[180:181] op_sel_hi:[1,0]
	v_pk_mul_f32 v[150:151], v[66:67], v[212:213] op_sel_hi:[1,0]
	v_pk_fma_f32 v[142:143], v[66:67], v[204:205], v[66:67] op_sel_hi:[1,0,1] neg_lo:[1,0,0] neg_hi:[1,0,0]
	ds_read_b128 v[172:175], v152 offset:19200
	v_pk_fma_f32 v[96:97], v[20:21], v[180:181], v[96:97] op_sel:[0,1,0]
	v_pk_fma_f32 v[150:151], v[20:21], v[212:213], v[150:151] op_sel:[0,1,0]
	v_pk_fma_f32 v[144:145], v[20:21], v[204:205], v[20:21] op_sel:[0,1,0] neg_lo:[1,0,0] neg_hi:[1,0,0]
	ds_read_b128 v[164:167], v152 offset:18688
	v_pk_fma_f32 v[96:97], v[68:69], v[182:183], v[96:97] op_sel_hi:[1,0,1]
	v_pk_fma_f32 v[150:151], v[68:69], v[214:215], v[150:151] op_sel_hi:[1,0,1]
	v_pk_fma_f32 v[146:147], v[68:69], v[206:207], v[68:69] op_sel_hi:[1,0,1] neg_lo:[1,0,0] neg_hi:[1,0,0]
	ds_read2st64_b64 v[240:243], v153 offset0:38 offset1:41
	v_pk_fma_f32 v[96:97], v[70:71], v[182:183], v[96:97] op_sel:[0,1,0]
	v_pk_fma_f32 v[150:151], v[70:71], v[214:215], v[150:151] op_sel:[0,1,0]
	v_pk_fma_f32 v[148:149], v[70:71], v[206:207], v[70:71] op_sel:[0,1,0] neg_lo:[1,0,0] neg_hi:[1,0,0]
	ds_read_b128 v[168:171], v152 offset:18944
	v_pk_fma_f32 v[142:143], v[248:249], v[208:209], v[142:143] op_sel_hi:[1,0,1]
	v_pk_fma_f32 v[144:145], v[248:249], v[208:209], v[144:145] op_sel:[0,1,0]
	v_add_f32_dpp v150, v150, v150 quad_perm:[1,0,3,2] row_mask:0xf bank_mask:0xf bound_ctrl:1
	v_add_f32_dpp v151, v151, v151 quad_perm:[1,0,3,2] row_mask:0xf bank_mask:0xf bound_ctrl:1
	v_pk_fma_f32 v[146:147], v[248:249], v[210:211], v[146:147] op_sel_hi:[1,0,1]
	v_add_f32_dpp v150, v150, v150 quad_perm:[2,3,0,1] row_mask:0xf bank_mask:0xf bound_ctrl:1
	v_add_f32_dpp v151, v151, v151 quad_perm:[2,3,0,1] row_mask:0xf bank_mask:0xf bound_ctrl:1
	v_pk_fma_f32 v[148:149], v[248:249], v[210:211], v[148:149] op_sel:[0,1,0]
	v_add_f32_dpp v150, v150, v150 row_half_mirror row_mask:0xf bank_mask:0xf bound_ctrl:1
	v_add_f32_dpp v151, v151, v151 row_half_mirror row_mask:0xf bank_mask:0xf bound_ctrl:1
	ds_read_b128 v[192:195], v152 offset:20736
	v_add_f32_dpp v150, v150, v150 row_mirror row_mask:0xf bank_mask:0xf bound_ctrl:1
	v_add_f32_dpp v151, v151, v151 row_mirror row_mask:0xf bank_mask:0xf bound_ctrl:1
	ds_read_b128 v[184:187], v152 offset:20224
	ds_read_b128 v[176:179], v152 offset:19456
	ds_read_b128 v[188:191], v152 offset:20480
	ds_read_b128 v[196:199], v152 offset:20992
	ds_read_b128 v[160:163], v152 offset:18432
	ds_read_b128 v[180:183], v152 offset:19968
	v_pk_fma_f32 v[66:67], v[150:151], v[216:217], v[142:143] op_sel_hi:[1,0,1]
	v_pk_fma_f32 v[20:21], v[150:151], v[216:217], v[144:145] op_sel:[0,1,0]
	v_pk_fma_f32 v[68:69], v[150:151], v[218:219], v[146:147] op_sel_hi:[1,0,1]
	v_pk_fma_f32 v[70:71], v[150:151], v[218:219], v[148:149] op_sel:[0,1,0]
	v_pk_mul_f32 v[98:99], v[66:67], v[200:201] op_sel_hi:[1,0]
	v_pk_mul_f32 v[150:151], v[66:67], v[232:233] op_sel_hi:[1,0]
	v_pk_fma_f32 v[142:143], v[66:67], v[224:225], v[66:67] op_sel_hi:[1,0,1] neg_lo:[1,0,0] neg_hi:[1,0,0]
	v_pk_fma_f32 v[98:99], v[20:21], v[200:201], v[98:99] op_sel:[0,1,0]
	v_pk_fma_f32 v[150:151], v[20:21], v[232:233], v[150:151] op_sel:[0,1,0]
	v_pk_fma_f32 v[144:145], v[20:21], v[224:225], v[20:21] op_sel:[0,1,0] neg_lo:[1,0,0] neg_hi:[1,0,0]
	v_pk_fma_f32 v[98:99], v[68:69], v[202:203], v[98:99] op_sel_hi:[1,0,1]
	v_pk_fma_f32 v[150:151], v[68:69], v[234:235], v[150:151] op_sel_hi:[1,0,1]
	v_pk_fma_f32 v[146:147], v[68:69], v[226:227], v[68:69] op_sel_hi:[1,0,1] neg_lo:[1,0,0] neg_hi:[1,0,0]
	v_pk_fma_f32 v[98:99], v[70:71], v[202:203], v[98:99] op_sel:[0,1,0]
	v_pk_fma_f32 v[150:151], v[70:71], v[234:235], v[150:151] op_sel:[0,1,0]
	v_pk_fma_f32 v[148:149], v[70:71], v[226:227], v[70:71] op_sel:[0,1,0] neg_lo:[1,0,0] neg_hi:[1,0,0]
	v_pk_fma_f32 v[142:143], v[250:251], v[228:229], v[142:143] op_sel_hi:[1,0,1]
	v_pk_fma_f32 v[144:145], v[250:251], v[228:229], v[144:145] op_sel:[0,1,0]
	v_add_f32_dpp v150, v150, v150 quad_perm:[1,0,3,2] row_mask:0xf bank_mask:0xf bound_ctrl:1
	v_add_f32_dpp v151, v151, v151 quad_perm:[1,0,3,2] row_mask:0xf bank_mask:0xf bound_ctrl:1
	v_pk_fma_f32 v[146:147], v[250:251], v[230:231], v[146:147] op_sel_hi:[1,0,1]
	v_add_f32_dpp v150, v150, v150 quad_perm:[2,3,0,1] row_mask:0xf bank_mask:0xf bound_ctrl:1
	v_add_f32_dpp v151, v151, v151 quad_perm:[2,3,0,1] row_mask:0xf bank_mask:0xf bound_ctrl:1
	v_pk_fma_f32 v[148:149], v[250:251], v[230:231], v[148:149] op_sel:[0,1,0]
	v_add_f32_dpp v150, v150, v150 row_half_mirror row_mask:0xf bank_mask:0xf bound_ctrl:1
	v_add_f32_dpp v151, v151, v151 row_half_mirror row_mask:0xf bank_mask:0xf bound_ctrl:1
	s_nop 0
	s_waitcnt lgkmcnt(0)
; #define LAS __attribute__((address_space(3)))
; #define ROW16_SUM4(x, y, z, w) do { DPP4(x, y, z, w, "quad_perm:[1,0,3,2]", "s_nop 1"); DPP4(x, y, z, w, "quad_perm:[2,3,0,1]", ""); DPP4(x, y, z, w, "row_half_mirror", ""); DPP4(x, y, z, w, "row_mirror", ""); } while (0)
; template <bool SAMPLE>
; __device__ __forceinline__ void rwkv_unit(PR P, LAS float* lds, const int b, const int h, const int half, const int wv) {
;     ...
;                 for (int tt = 0; tt < GS; ++tt) {
;                     const LAS float* qn = q0 + (tt + 1 < GS ? tt + 1 : tt) * 384;
;                     const f32x4 nr4 = *(const LAS f32x4*)(qn + j0), no4 = *(const LAS f32x4*)(qn + 64 + j0), nk4 = *(const LAS f32x4*)(qn + 128 + j0), na4 = *(const LAS f32x4*)(qn + 192 + j0), nb4 = *(const LAS f32x4*)(qn + 256 + j0);
;                     const f32x2 nv2 = *(const LAS f32x2*)(qn + 320 + row0);
;                     f32x2 sa = (S[0] * a4[0] + S[1] * a4[1]) + (S[2] * a4[2] + S[3] * a4[3]);
;                     float sx = sa.x, sy = sa.y; ROW16_SUM4(sx, sy, py0, py1); sa = (f32x2){sx, sy};
;                     if (tt > 0) { yk0 = cgl == tt - 1 ? py0 : yk0; yk1 = cgl == tt - 1 ? py1 : yk1; }
; #pragma unroll
;                     for (int c = 0; c < 4; ++c) { f32x2 t = S[c] - S[c] * o4[c]; t = t + sa * b4[c]; S[c] = t + v2 * k4[c]; }
;                     const f32x2 y = (S[0] * r4[0] + S[1] * r4[1]) + (S[2] * r4[2] + S[3] * r4[3]);
;                     py0 = y.x; py1 = y.y;
;                     r4 = nr4; o4 = no4; k4 = nk4; a4 = na4; b4 = nb4; v2 = nv2;
	v_add_f32_dpp v150, v150, v150 row_mirror row_mask:0xf bank_mask:0xf bound_ctrl:1
	v_add_f32_dpp v151, v151, v151 row_mirror row_mask:0xf bank_mask:0xf bound_ctrl:1
	v_pk_fma_f32 v[66:67], v[150:151], v[236:237], v[142:143] op_sel_hi:[1,0,1]
	v_pk_fma_f32 v[20:21], v[150:151], v[236:237], v[144:145] op_sel:[0,1,0]
	v_pk_fma_f32 v[68:69], v[150:151], v[238:239], v[146:147] op_sel_hi:[1,0,1]
	v_pk_fma_f32 v[70:71], v[150:151], v[238:239], v[148:149] op_sel:[0,1,0]
	v_pk_mul_f32 v[100:101], v[66:67], v[220:221] op_sel_hi:[1,0]
	v_pk_mul_f32 v[150:151], v[66:67], v[172:173] op_sel_hi:[1,0]
	v_pk_fma_f32 v[142:143], v[66:67], v[164:165], v[66:67] op_sel_hi:[1,0,1] neg_lo:[1,0,0] neg_hi:[1,0,0]
	ds_read_b128 v[212:215], v152 offset:22272
	v_pk_fma_f32 v[100:101], v[20:21], v[220:221], v[100:101] op_sel:[0,1,0]
	v_pk_fma_f32 v[150:151], v[20:21], v[172:173], v[150:151] op_sel:[0,1,0]
	v_pk_fma_f32 v[144:145], v[20:21], v[164:165], v[20:21] op_sel:[0,1,0] neg_lo:[1,0,0] neg_hi:[1,0,0]
	ds_read_b128 v[204:207], v152 offset:21760
	v_pk_fma_f32 v[100:101], v[68:69], v[222:223], v[100:101] op_sel_hi:[1,0,1]
	v_pk_fma_f32 v[150:151], v[68:69], v[174:175], v[150:151] op_sel_hi:[1,0,1]
	v_pk_fma_f32 v[146:147], v[68:69], v[166:167], v[68:69] op_sel_hi:[1,0,1] neg_lo:[1,0,0] neg_hi:[1,0,0]
	ds_read2st64_b64 v[244:247], v153 offset0:44 offset1:47
	v_pk_fma_f32 v[100:101], v[70:71], v[222:223], v[100:101] op_sel:[0,1,0]
	v_pk_fma_f32 v[150:151], v[70:71], v[174:175], v[150:151] op_sel:[0,1,0]
	v_pk_fma_f32 v[148:149], v[70:71], v[166:167], v[70:71] op_sel:[0,1,0] neg_lo:[1,0,0] neg_hi:[1,0,0]
	ds_read_b128 v[208:211], v152 offset:22016
	v_pk_fma_f32 v[142:143], v[240:241], v[168:169], v[142:143] op_sel_hi:[1,0,1]
	v_pk_fma_f32 v[144:145], v[240:241], v[168:169], v[144:145] op_sel:[0,1,0]
	v_add_f32_dpp v150, v150, v150 quad_perm:[1,0,3,2] row_mask:0xf bank_mask:0xf bound_ctrl:1
	v_add_f32_dpp v151, v151, v151 quad_perm:[1,0,3,2] row_mask:0xf bank_mask:0xf bound_ctrl:1
	v_pk_fma_f32 v[146:147], v[240:241], v[170:171], v[146:147] op_sel_hi:[1,0,1]
	v_add_f32_dpp v150, v150, v150 quad_perm:[2,3,0,1] row_mask:0xf bank_mask:0xf bound_ctrl:1
	v_add_f32_dpp v151, v151, v151 quad_perm:[2,3,0,1] row_mask:0xf bank_mask:0xf bound_ctrl:1
	v_pk_fma_f32 v[148:149], v[240:241], v[170:171], v[148:149] op_sel:[0,1,0]
	v_add_f32_dpp v150, v150, v150 row_half_mirror row_mask:0xf bank_mask:0xf bound_ctrl:1
	v_add_f32_dpp v151, v151, v151 row_half_mirror row_mask:0xf bank_mask:0xf bound_ctrl:1
	ds_read_b128 v[232:235], v152 offset:23808
	v_add_f32_dpp v150, v150, v150 row_mirror row_mask:0xf bank_mask:0xf bound_ctrl:1
	v_add_f32_dpp v151, v151, v151 row_mirror row_mask:0xf bank_mask:0xf bound_ctrl:1
	ds_read_b128 v[224:227], v152 offset:23296
	ds_read_b128 v[216:219], v152 offset:22528
	ds_read_b128 v[228:231], v152 offset:23552
	ds_read_b128 v[236:239], v152 offset:24064
	ds_read_b128 v[200:203], v152 offset:21504
	ds_read_b128 v[220:223], v152 offset:23040
	v_pk_fma_f32 v[66:67], v[150:151], v[176:177], v[142:143] op_sel_hi:[1,0,1]
	v_pk_fma_f32 v[20:21], v[150:151], v[176:177], v[144:145] op_sel:[0,1,0]
	v_pk_fma_f32 v[68:69], v[150:151], v[178:179], v[146:147] op_sel_hi:[1,0,1]
	v_pk_fma_f32 v[70:71], v[150:151], v[178:179], v[148:149] op_sel:[0,1,0]
	v_pk_mul_f32 v[102:103], v[66:67], v[160:161] op_sel_hi:[1,0]
	v_pk_mul_f32 v[150:151], v[66:67], v[192:193] op_sel_hi:[1,0]
	v_pk_fma_f32 v[142:143], v[66:67], v[184:185], v[66:67] op_sel_hi:[1,0,1] neg_lo:[1,0,0] neg_hi:[1,0,0]
	v_pk_fma_f32 v[102:103], v[20:21], v[160:161], v[102:103] op_sel:[0,1,0]
	v_pk_fma_f32 v[150:151], v[20:21], v[192:193], v[150:151] op_sel:[0,1,0]
	v_pk_fma_f32 v[144:145], v[20:21], v[184:185], v[20:21] op_sel:[0,1,0] neg_lo:[1,0,0] neg_hi:[1,0,0]
	v_pk_fma_f32 v[102:103], v[68:69], v[162:163], v[102:103] op_sel_hi:[1,0,1]
	v_pk_fma_f32 v[150:151], v[68:69], v[194:195], v[150:151] op_sel_hi:[1,0,1]
	v_pk_fma_f32 v[146:147], v[68:69], v[186:187], v[68:69] op_sel_hi:[1,0,1] neg_lo:[1,0,0] neg_hi:[1,0,0]
	v_pk_fma_f32 v[102:103], v[70:71], v[162:163], v[102:103] op_sel:[0,1,0]
	v_pk_fma_f32 v[150:151], v[70:71], v[194:195], v[150:151] op_sel:[0,1,0]
	v_pk_fma_f32 v[148:149], v[70:71], v[186:187], v[70:71] op_sel:[0,1,0] neg_lo:[1,0,0] neg_hi:[1,0,0]
	v_pk_fma_f32 v[142:143], v[242:243], v[188:189], v[142:143] op_sel_hi:[1,0,1]
	v_pk_fma_f32 v[144:145], v[242:243], v[188:189], v[144:145] op_sel:[0,1,0]
	v_add_f32_dpp v150, v150, v150 quad_perm:[1,0,3,2] row_mask:0xf bank_mask:0xf bound_ctrl:1
	v_add_f32_dpp v151, v151, v151 quad_perm:[1,0,3,2] row_mask:0xf bank_mask:0xf bound_ctrl:1
	v_pk_fma_f32 v[146:147], v[242:243], v[190:191], v[146:147] op_sel_hi:[1,0,1]
	v_add_f32_dpp v150, v150, v150 quad_perm:[2,3,0,1] row_mask:0xf bank_mask:0xf bound_ctrl:1
	v_add_f32_dpp v151, v151, v151 quad_perm:[2,3,0,1] row_mask:0xf bank_mask:0xf bound_ctrl:1
	v_pk_fma_f32 v[148:149], v[242:243], v[190:191], v[148:149] op_sel:[0,1,0]
	v_add_f32_dpp v150, v150, v150 row_half_mirror row_mask:0xf bank_mask:0xf bound_ctrl:1
	v_add_f32_dpp v151, v151, v151 row_half_mirror row_mask:0xf bank_mask:0xf bound_ctrl:1
	s_nop 0
	s_waitcnt lgkmcnt(0)
; #define LAS __attribute__((address_space(3)))
; #define ROW16_SUM4(x, y, z, w) do { DPP4(x, y, z, w, "quad_perm:[1,0,3,2]", "s_nop 1"); DPP4(x, y, z, w, "quad_perm:[2,3,0,1]", ""); DPP4(x, y, z, w, "row_half_mirror", ""); DPP4(x, y, z, w, "row_mirror", ""); } while (0)
; template <bool SAMPLE>
; __device__ __forceinline__ void rwkv_unit(PR P, LAS float* lds, const int b, const int h, const int half, const int wv) {
;     ...
;                 for (int tt = 0; tt < GS; ++tt) {
;                     const LAS float* qn = q0 + (tt + 1 < GS ? tt + 1 : tt) * 384;
;                     const f32x4 nr4 = *(const LAS f32x4*)(qn + j0), no4 = *(const LAS f32x4*)(qn + 64 + j0), nk4 = *(const LAS f32x4*)(qn + 128 + j0), na4 = *(const LAS f32x4*)(qn + 192 + j0), nb4 = *(const LAS f32x4*)(qn + 256 + j0);
;                     const f32x2 nv2 = *(const LAS f32x2*)(qn + 320 + row0);
;                     f32x2 sa = (S[0] * a4[0] + S[1] * a4[1]) + (S[2] * a4[2] + S[3] * a4[3]);
;                     float sx = sa.x, sy = sa.y; ROW16_SUM4(sx, sy, py0, py1); sa = (f32x2){sx, sy};
;                     if (tt > 0) { yk0 = cgl == tt - 1 ? py0 : yk0; yk1 = cgl == tt - 1 ? py1 : yk1; }
; #pragma unroll
;                     for (int c = 0; c < 4; ++c) { f32x2 t = S[c] - S[c] * o4[c]; t = t + sa * b4[c]; S[c] = t + v2 * k4[c]; }
;                     const f32x2 y = (S[0] * r4[0] + S[1] * r4[1]) + (S[2] * r4[2] + S[3] * r4[3]);
;                     py0 = y.x; py1 = y.y;
;                     r4 = nr4; o4 = no4; k4 = nk4; a4 = na4; b4 = nb4; v2 = nv2;
	v_add_f32_dpp v150, v150, v150 row_mirror row_mask:0xf bank_mask:0xf bound_ctrl:1
	v_add_f32_dpp v151, v151, v151 row_mirror row_mask:0xf bank_mask:0xf bound_ctrl:1
	v_pk_fma_f32 v[66:67], v[150:151], v[196:197], v[142:143] op_sel_hi:[1,0,1]
	v_pk_fma_f32 v[20:21], v[150:151], v[196:197], v[144:145] op_sel:[0,1,0]
	v_pk_fma_f32 v[68:69], v[150:151], v[198:199], v[146:147] op_sel_hi:[1,0,1]
	v_pk_fma_f32 v[70:71], v[150:151], v[198:199], v[148:149] op_sel:[0,1,0]
	v_pk_mul_f32 v[104:105], v[66:67], v[180:181] op_sel_hi:[1,0]
	v_pk_mul_f32 v[150:151], v[66:67], v[212:213] op_sel_hi:[1,0]
	v_pk_fma_f32 v[142:143], v[66:67], v[204:205], v[66:67] op_sel_hi:[1,0,1] neg_lo:[1,0,0] neg_hi:[1,0,0]
	ds_read_b128 v[172:175], v152 offset:25344
	v_pk_fma_f32 v[104:105], v[20:21], v[180:181], v[104:105] op_sel:[0,1,0]
	v_pk_fma_f32 v[150:151], v[20:21], v[212:213], v[150:151] op_sel:[0,1,0]
	v_pk_fma_f32 v[144:145], v[20:21], v[204:205], v[20:21] op_sel:[0,1,0] neg_lo:[1,0,0] neg_hi:[1,0,0]
	ds_read_b128 v[164:167], v152 offset:24832
	v_pk_fma_f32 v[104:105], v[68:69], v[182:183], v[104:105] op_sel_hi:[1,0,1]
	v_pk_fma_f32 v[150:151], v[68:69], v[214:215], v[150:151] op_sel_hi:[1,0,1]
	v_pk_fma_f32 v[146:147], v[68:69], v[206:207], v[68:69] op_sel_hi:[1,0,1] neg_lo:[1,0,0] neg_hi:[1,0,0]
	ds_read2st64_b64 v[248:251], v153 offset0:50 offset1:53
	v_pk_fma_f32 v[104:105], v[70:71], v[182:183], v[104:105] op_sel:[0,1,0]
	v_pk_fma_f32 v[150:151], v[70:71], v[214:215], v[150:151] op_sel:[0,1,0]
	v_pk_fma_f32 v[148:149], v[70:71], v[206:207], v[70:71] op_sel:[0,1,0] neg_lo:[1,0,0] neg_hi:[1,0,0]
	ds_read_b128 v[168:171], v152 offset:25088
	v_pk_fma_f32 v[142:143], v[244:245], v[208:209], v[142:143] op_sel_hi:[1,0,1]
	v_pk_fma_f32 v[144:145], v[244:245], v[208:209], v[144:145] op_sel:[0,1,0]
	v_add_f32_dpp v150, v150, v150 quad_perm:[1,0,3,2] row_mask:0xf bank_mask:0xf bound_ctrl:1
	v_add_f32_dpp v151, v151, v151 quad_perm:[1,0,3,2] row_mask:0xf bank_mask:0xf bound_ctrl:1
	v_pk_fma_f32 v[146:147], v[244:245], v[210:211], v[146:147] op_sel_hi:[1,0,1]
	v_add_f32_dpp v150, v150, v150 quad_perm:[2,3,0,1] row_mask:0xf bank_mask:0xf bound_ctrl:1
	v_add_f32_dpp v151, v151, v151 quad_perm:[2,3,0,1] row_mask:0xf bank_mask:0xf bound_ctrl:1
	v_pk_fma_f32 v[148:149], v[244:245], v[210:211], v[148:149] op_sel:[0,1,0]
	v_add_f32_dpp v150, v150, v150 row_half_mirror row_mask:0xf bank_mask:0xf bound_ctrl:1
	v_add_f32_dpp v151, v151, v151 row_half_mirror row_mask:0xf bank_mask:0xf bound_ctrl:1
	ds_read_b128 v[192:195], v152 offset:26880
	v_add_f32_dpp v150, v150, v150 row_mirror row_mask:0xf bank_mask:0xf bound_ctrl:1
	v_add_f32_dpp v151, v151, v151 row_mirror row_mask:0xf bank_mask:0xf bound_ctrl:1
	ds_read_b128 v[184:187], v152 offset:26368
	ds_read_b128 v[176:179], v152 offset:25600
	ds_read_b128 v[188:191], v152 offset:26624
	ds_read_b128 v[196:199], v152 offset:27136
	ds_read_b128 v[160:163], v152 offset:24576
	ds_read_b128 v[180:183], v152 offset:26112
	v_pk_fma_f32 v[66:67], v[150:151], v[216:217], v[142:143] op_sel_hi:[1,0,1]
	v_pk_fma_f32 v[20:21], v[150:151], v[216:217], v[144:145] op_sel:[0,1,0]
	v_pk_fma_f32 v[68:69], v[150:151], v[218:219], v[146:147] op_sel_hi:[1,0,1]
	v_pk_fma_f32 v[70:71], v[150:151], v[218:219], v[148:149] op_sel:[0,1,0]
	v_pk_mul_f32 v[106:107], v[66:67], v[200:201] op_sel_hi:[1,0]
	v_pk_mul_f32 v[150:151], v[66:67], v[232:233] op_sel_hi:[1,0]
	v_pk_fma_f32 v[142:143], v[66:67], v[224:225], v[66:67] op_sel_hi:[1,0,1] neg_lo:[1,0,0] neg_hi:[1,0,0]
	v_pk_fma_f32 v[106:107], v[20:21], v[200:201], v[106:107] op_sel:[0,1,0]
	v_pk_fma_f32 v[150:151], v[20:21], v[232:233], v[150:151] op_sel:[0,1,0]
	v_pk_fma_f32 v[144:145], v[20:21], v[224:225], v[20:21] op_sel:[0,1,0] neg_lo:[1,0,0] neg_hi:[1,0,0]
	v_pk_fma_f32 v[106:107], v[68:69], v[202:203], v[106:107] op_sel_hi:[1,0,1]
	v_pk_fma_f32 v[150:151], v[68:69], v[234:235], v[150:151] op_sel_hi:[1,0,1]
	v_pk_fma_f32 v[146:147], v[68:69], v[226:227], v[68:69] op_sel_hi:[1,0,1] neg_lo:[1,0,0] neg_hi:[1,0,0]
	v_pk_fma_f32 v[106:107], v[70:71], v[202:203], v[106:107] op_sel:[0,1,0]
	v_pk_fma_f32 v[150:151], v[70:71], v[234:235], v[150:151] op_sel:[0,1,0]
	v_pk_fma_f32 v[148:149], v[70:71], v[226:227], v[70:71] op_sel:[0,1,0] neg_lo:[1,0,0] neg_hi:[1,0,0]
	v_pk_fma_f32 v[142:143], v[246:247], v[228:229], v[142:143] op_sel_hi:[1,0,1]
	v_pk_fma_f32 v[144:145], v[246:247], v[228:229], v[144:145] op_sel:[0,1,0]
	v_add_f32_dpp v150, v150, v150 quad_perm:[1,0,3,2] row_mask:0xf bank_mask:0xf bound_ctrl:1
	v_add_f32_dpp v151, v151, v151 quad_perm:[1,0,3,2] row_mask:0xf bank_mask:0xf bound_ctrl:1
	v_pk_fma_f32 v[146:147], v[246:247], v[230:231], v[146:147] op_sel_hi:[1,0,1]
	v_add_f32_dpp v150, v150, v150 quad_perm:[2,3,0,1] row_mask:0xf bank_mask:0xf bound_ctrl:1
	v_add_f32_dpp v151, v151, v151 quad_perm:[2,3,0,1] row_mask:0xf bank_mask:0xf bound_ctrl:1
	v_pk_fma_f32 v[148:149], v[246:247], v[230:231], v[148:149] op_sel:[0,1,0]
	v_add_f32_dpp v150, v150, v150 row_half_mirror row_mask:0xf bank_mask:0xf bound_ctrl:1
	v_add_f32_dpp v151, v151, v151 row_half_mirror row_mask:0xf bank_mask:0xf bound_ctrl:1
	s_nop 0
	s_waitcnt lgkmcnt(0)
; #define LAS __attribute__((address_space(3)))
; #define ROW16_SUM4(x, y, z, w) do { DPP4(x, y, z, w, "quad_perm:[1,0,3,2]", "s_nop 1"); DPP4(x, y, z, w, "quad_perm:[2,3,0,1]", ""); DPP4(x, y, z, w, "row_half_mirror", ""); DPP4(x, y, z, w, "row_mirror", ""); } while (0)
; #define ROW16_SUM2(x, y) do { DPP2(x, y, "quad_perm:[1,0,3,2]", "s_nop 1"); DPP2(x, y, "quad_perm:[2,3,0,1]", "s_nop 0"); DPP2(x, y, "row_half_mirror", "s_nop 0"); DPP2(x, y, "row_mirror", "s_nop 0"); } while (0)
; template <bool SAMPLE>
; __device__ __forceinline__ void rwkv_unit(PR P, LAS float* lds, const int b, const int h, const int half, const int wv) {
;     ...
;                 for (int tt = 0; tt < GS; ++tt) {
;                     const LAS float* qn = q0 + (tt + 1 < GS ? tt + 1 : tt) * 384;
;                     const f32x4 nr4 = *(const LAS f32x4*)(qn + j0), no4 = *(const LAS f32x4*)(qn + 64 + j0), nk4 = *(const LAS f32x4*)(qn + 128 + j0), na4 = *(const LAS f32x4*)(qn + 192 + j0), nb4 = *(const LAS f32x4*)(qn + 256 + j0);
;                     const f32x2 nv2 = *(const LAS f32x2*)(qn + 320 + row0);
;                     f32x2 sa = (S[0] * a4[0] + S[1] * a4[1]) + (S[2] * a4[2] + S[3] * a4[3]);
;                     float sx = sa.x, sy = sa.y; ROW16_SUM4(sx, sy, py0, py1); sa = (f32x2){sx, sy};
;                     if (tt > 0) { yk0 = cgl == tt - 1 ? py0 : yk0; yk1 = cgl == tt - 1 ? py1 : yk1; }
; #pragma unroll
;                     for (int c = 0; c < 4; ++c) { f32x2 t = S[c] - S[c] * o4[c]; t = t + sa * b4[c]; S[c] = t + v2 * k4[c]; }
;                     const f32x2 y = (S[0] * r4[0] + S[1] * r4[1]) + (S[2] * r4[2] + S[3] * r4[3]);
;                     py0 = y.x; py1 = y.y;
;                     r4 = nr4; o4 = no4; k4 = nk4; a4 = na4; b4 = nb4; v2 = nv2;
;                 }
;                 ROW16_SUM2(py0, py1); yk0 = cgl == GS - 1 ? py0 : yk0; yk1 = cgl == GS - 1 ? py1 : yk1;
	v_add_f32_dpp v150, v150, v150 row_mirror row_mask:0xf bank_mask:0xf bound_ctrl:1
	v_add_f32_dpp v151, v151, v151 row_mirror row_mask:0xf bank_mask:0xf bound_ctrl:1
	v_pk_fma_f32 v[66:67], v[150:151], v[236:237], v[142:143] op_sel_hi:[1,0,1]
	v_pk_fma_f32 v[20:21], v[150:151], v[236:237], v[144:145] op_sel:[0,1,0]
	v_pk_fma_f32 v[68:69], v[150:151], v[238:239], v[146:147] op_sel_hi:[1,0,1]
	v_pk_fma_f32 v[70:71], v[150:151], v[238:239], v[148:149] op_sel:[0,1,0]
	v_pk_mul_f32 v[108:109], v[66:67], v[220:221] op_sel_hi:[1,0]
	v_pk_mul_f32 v[150:151], v[66:67], v[172:173] op_sel_hi:[1,0]
	v_pk_fma_f32 v[142:143], v[66:67], v[164:165], v[66:67] op_sel_hi:[1,0,1] neg_lo:[1,0,0] neg_hi:[1,0,0]
	ds_read_b128 v[212:215], v152 offset:28416
	v_pk_fma_f32 v[108:109], v[20:21], v[220:221], v[108:109] op_sel:[0,1,0]
	v_pk_fma_f32 v[150:151], v[20:21], v[172:173], v[150:151] op_sel:[0,1,0]
	v_pk_fma_f32 v[144:145], v[20:21], v[164:165], v[20:21] op_sel:[0,1,0] neg_lo:[1,0,0] neg_hi:[1,0,0]
	ds_read_b128 v[204:207], v152 offset:27904
	v_pk_fma_f32 v[108:109], v[68:69], v[222:223], v[108:109] op_sel_hi:[1,0,1]
	v_pk_fma_f32 v[150:151], v[68:69], v[174:175], v[150:151] op_sel_hi:[1,0,1]
	v_pk_fma_f32 v[146:147], v[68:69], v[166:167], v[68:69] op_sel_hi:[1,0,1] neg_lo:[1,0,0] neg_hi:[1,0,0]
	ds_read2st64_b64 v[240:243], v153 offset0:56 offset1:59
	v_pk_fma_f32 v[108:109], v[70:71], v[222:223], v[108:109] op_sel:[0,1,0]
	v_pk_fma_f32 v[150:151], v[70:71], v[174:175], v[150:151] op_sel:[0,1,0]
	v_pk_fma_f32 v[148:149], v[70:71], v[166:167], v[70:71] op_sel:[0,1,0] neg_lo:[1,0,0] neg_hi:[1,0,0]
	ds_read_b128 v[208:211], v152 offset:28160
	v_pk_fma_f32 v[142:143], v[248:249], v[168:169], v[142:143] op_sel_hi:[1,0,1]
	v_pk_fma_f32 v[144:145], v[248:249], v[168:169], v[144:145] op_sel:[0,1,0]
	v_add_f32_dpp v150, v150, v150 quad_perm:[1,0,3,2] row_mask:0xf bank_mask:0xf bound_ctrl:1
	v_add_f32_dpp v151, v151, v151 quad_perm:[1,0,3,2] row_mask:0xf bank_mask:0xf bound_ctrl:1
	v_pk_fma_f32 v[146:147], v[248:249], v[170:171], v[146:147] op_sel_hi:[1,0,1]
	v_add_f32_dpp v150, v150, v150 quad_perm:[2,3,0,1] row_mask:0xf bank_mask:0xf bound_ctrl:1
	v_add_f32_dpp v151, v151, v151 quad_perm:[2,3,0,1] row_mask:0xf bank_mask:0xf bound_ctrl:1
	v_pk_fma_f32 v[148:149], v[248:249], v[170:171], v[148:149] op_sel:[0,1,0]
	v_add_f32_dpp v150, v150, v150 row_half_mirror row_mask:0xf bank_mask:0xf bound_ctrl:1
	v_add_f32_dpp v151, v151, v151 row_half_mirror row_mask:0xf bank_mask:0xf bound_ctrl:1
	ds_read_b128 v[232:235], v152 offset:29952
	v_add_f32_dpp v150, v150, v150 row_mirror row_mask:0xf bank_mask:0xf bound_ctrl:1
	v_add_f32_dpp v151, v151, v151 row_mirror row_mask:0xf bank_mask:0xf bound_ctrl:1
	ds_read_b128 v[224:227], v152 offset:29440
	ds_read_b128 v[216:219], v152 offset:28672
	ds_read_b128 v[228:231], v152 offset:29696
	ds_read_b128 v[236:239], v152 offset:30208
	ds_read_b128 v[200:203], v152 offset:27648
	ds_read_b128 v[220:223], v152 offset:29184
	v_pk_fma_f32 v[66:67], v[150:151], v[176:177], v[142:143] op_sel_hi:[1,0,1]
	v_pk_fma_f32 v[20:21], v[150:151], v[176:177], v[144:145] op_sel:[0,1,0]
	v_pk_fma_f32 v[68:69], v[150:151], v[178:179], v[146:147] op_sel_hi:[1,0,1]
	v_pk_fma_f32 v[70:71], v[150:151], v[178:179], v[148:149] op_sel:[0,1,0]
	v_add_f32_dpp v78, v78, v78 row_ror:8 row_mask:0xf bank_mask:0x3 bound_ctrl:1
	v_add_f32_dpp v78, v94, v94 row_ror:8 row_mask:0xf bank_mask:0xc bound_ctrl:1
	v_add_f32_dpp v80, v80, v80 row_ror:8 row_mask:0xf bank_mask:0x3 bound_ctrl:1
	v_add_f32_dpp v80, v96, v96 row_ror:8 row_mask:0xf bank_mask:0xc bound_ctrl:1
	v_add_f32_dpp v82, v82, v82 row_ror:8 row_mask:0xf bank_mask:0x3 bound_ctrl:1
	v_add_f32_dpp v82, v98, v98 row_ror:8 row_mask:0xf bank_mask:0xc bound_ctrl:1
	v_add_f32_dpp v84, v84, v84 row_ror:8 row_mask:0xf bank_mask:0x3 bound_ctrl:1
	v_add_f32_dpp v84, v100, v100 row_ror:8 row_mask:0xf bank_mask:0xc bound_ctrl:1
	v_add_f32_dpp v86, v86, v86 row_ror:8 row_mask:0xf bank_mask:0x3 bound_ctrl:1
	v_add_f32_dpp v86, v102, v102 row_ror:8 row_mask:0xf bank_mask:0xc bound_ctrl:1
	v_add_f32_dpp v88, v88, v88 row_ror:8 row_mask:0xf bank_mask:0x3 bound_ctrl:1
	v_add_f32_dpp v88, v104, v104 row_ror:8 row_mask:0xf bank_mask:0xc bound_ctrl:1
	v_add_f32_dpp v90, v90, v90 row_ror:8 row_mask:0xf bank_mask:0x3 bound_ctrl:1
	v_add_f32_dpp v90, v106, v106 row_ror:8 row_mask:0xf bank_mask:0xc bound_ctrl:1
	v_add_f32_dpp v92, v92, v92 row_ror:8 row_mask:0xf bank_mask:0x3 bound_ctrl:1
	v_add_f32_dpp v92, v108, v108 row_ror:8 row_mask:0xf bank_mask:0xc bound_ctrl:1
	v_add_f32_dpp v79, v79, v79 row_ror:8 row_mask:0xf bank_mask:0x3 bound_ctrl:1
	v_add_f32_dpp v79, v95, v95 row_ror:8 row_mask:0xf bank_mask:0xc bound_ctrl:1
	v_add_f32_dpp v81, v81, v81 row_ror:8 row_mask:0xf bank_mask:0x3 bound_ctrl:1
	v_add_f32_dpp v81, v97, v97 row_ror:8 row_mask:0xf bank_mask:0xc bound_ctrl:1
	v_add_f32_dpp v83, v83, v83 row_ror:8 row_mask:0xf bank_mask:0x3 bound_ctrl:1
	v_add_f32_dpp v83, v99, v99 row_ror:8 row_mask:0xf bank_mask:0xc bound_ctrl:1
	v_add_f32_dpp v85, v85, v85 row_ror:8 row_mask:0xf bank_mask:0x3 bound_ctrl:1
	v_add_f32_dpp v85, v101, v101 row_ror:8 row_mask:0xf bank_mask:0xc bound_ctrl:1
	v_add_f32_dpp v87, v87, v87 row_ror:8 row_mask:0xf bank_mask:0x3 bound_ctrl:1
	v_add_f32_dpp v87, v103, v103 row_ror:8 row_mask:0xf bank_mask:0xc bound_ctrl:1
	v_add_f32_dpp v89, v89, v89 row_ror:8 row_mask:0xf bank_mask:0x3 bound_ctrl:1
	v_add_f32_dpp v89, v105, v105 row_ror:8 row_mask:0xf bank_mask:0xc bound_ctrl:1
	v_add_f32_dpp v91, v91, v91 row_ror:8 row_mask:0xf bank_mask:0x3 bound_ctrl:1
	v_add_f32_dpp v91, v107, v107 row_ror:8 row_mask:0xf bank_mask:0xc bound_ctrl:1
; __device__ __forceinline__ unsigned cvt_pk_bf16(float lo, float hi) { const f32x2_t v = {lo, hi}; const bf16x2_t b = __builtin_convertvector(v, bf16x2_t); return __builtin_bit_cast(unsigned, b); }
; #define ROW16_SUM2(x, y) do { DPP2(x, y, "quad_perm:[1,0,3,2]", "s_nop 1"); DPP2(x, y, "quad_perm:[2,3,0,1]", "s_nop 0"); DPP2(x, y, "row_half_mirror", "s_nop 0"); DPP2(x, y, "row_mirror", "s_nop 0"); } while (0)
; template <bool SAMPLE>
; __device__ __forceinline__ void rwkv_unit(PR P, LAS float* lds, const int b, const int h, const int half, const int wv) {
;     ...
;                     if (tt > 0) { yk0 = cgl == tt - 1 ? py0 : yk0; yk1 = cgl == tt - 1 ? py1 : yk1; }
; #pragma unroll
;                     for (int c = 0; c < 4; ++c) { f32x2 t = S[c] - S[c] * o4[c]; t = t + sa * b4[c]; S[c] = t + v2 * k4[c]; }
;                     const f32x2 y = (S[0] * r4[0] + S[1] * r4[1]) + (S[2] * r4[2] + S[3] * r4[3]);
;                     py0 = y.x; py1 = y.y;
;                     r4 = nr4; o4 = no4; k4 = nk4; a4 = na4; b4 = nb4; v2 = nv2;
;                 }
;                 ROW16_SUM2(py0, py1); yk0 = cgl == GS - 1 ? py0 : yk0; yk1 = cgl == GS - 1 ? py1 : yk1;
;                 if (cgl < GS) *(unsigned*)(YS + (size_t)(row_base + c * TC + g * GS + cgl) * 512 + h * 64 + row0) = pg8::cvt_pk_bf16(yk0, yk1);
	v_add_f32_dpp v93, v93, v93 row_ror:8 row_mask:0xf bank_mask:0x3 bound_ctrl:1
	v_add_f32_dpp v93, v109, v109 row_ror:8 row_mask:0xf bank_mask:0xc bound_ctrl:1
	v_add_f32_dpp v78, v78, v78 row_shl:4 row_mask:0xf bank_mask:0x5 bound_ctrl:1
	v_add_f32_dpp v78, v86, v86 row_shr:4 row_mask:0xf bank_mask:0xa bound_ctrl:1
	v_add_f32_dpp v80, v80, v80 row_shl:4 row_mask:0xf bank_mask:0x5 bound_ctrl:1
	v_add_f32_dpp v80, v88, v88 row_shr:4 row_mask:0xf bank_mask:0xa bound_ctrl:1
	v_add_f32_dpp v82, v82, v82 row_shl:4 row_mask:0xf bank_mask:0x5 bound_ctrl:1
	v_add_f32_dpp v82, v90, v90 row_shr:4 row_mask:0xf bank_mask:0xa bound_ctrl:1
	v_add_f32_dpp v84, v84, v84 row_shl:4 row_mask:0xf bank_mask:0x5 bound_ctrl:1
	v_add_f32_dpp v84, v92, v92 row_shr:4 row_mask:0xf bank_mask:0xa bound_ctrl:1
	v_add_f32_dpp v79, v79, v79 row_shl:4 row_mask:0xf bank_mask:0x5 bound_ctrl:1
	v_add_f32_dpp v79, v87, v87 row_shr:4 row_mask:0xf bank_mask:0xa bound_ctrl:1
	v_add_f32_dpp v81, v81, v81 row_shl:4 row_mask:0xf bank_mask:0x5 bound_ctrl:1
	v_add_f32_dpp v81, v89, v89 row_shr:4 row_mask:0xf bank_mask:0xa bound_ctrl:1
	v_add_f32_dpp v83, v83, v83 row_shl:4 row_mask:0xf bank_mask:0x5 bound_ctrl:1
	v_add_f32_dpp v83, v91, v91 row_shr:4 row_mask:0xf bank_mask:0xa bound_ctrl:1
	v_add_f32_dpp v85, v85, v85 row_shl:4 row_mask:0xf bank_mask:0x5 bound_ctrl:1
	v_add_f32_dpp v85, v93, v93 row_shr:4 row_mask:0xf bank_mask:0xa bound_ctrl:1
	v_add_f32_dpp v78, v78, v78 quad_perm:[1,0,3,2] row_mask:0xf bank_mask:0xf bound_ctrl:1
	v_add_f32_dpp v80, v80, v80 quad_perm:[1,0,3,2] row_mask:0xf bank_mask:0xf bound_ctrl:1
	v_add_f32_dpp v82, v82, v82 quad_perm:[1,0,3,2] row_mask:0xf bank_mask:0xf bound_ctrl:1
	v_add_f32_dpp v84, v84, v84 quad_perm:[1,0,3,2] row_mask:0xf bank_mask:0xf bound_ctrl:1
	v_add_f32_dpp v79, v79, v79 quad_perm:[1,0,3,2] row_mask:0xf bank_mask:0xf bound_ctrl:1
	v_add_f32_dpp v81, v81, v81 quad_perm:[1,0,3,2] row_mask:0xf bank_mask:0xf bound_ctrl:1
	v_add_f32_dpp v83, v83, v83 quad_perm:[1,0,3,2] row_mask:0xf bank_mask:0xf bound_ctrl:1
	v_add_f32_dpp v85, v85, v85 quad_perm:[1,0,3,2] row_mask:0xf bank_mask:0xf bound_ctrl:1
	v_add_f32_dpp v78, v78, v78 quad_perm:[2,3,0,1] row_mask:0xf bank_mask:0xf bound_ctrl:1
	v_add_f32_dpp v80, v80, v80 quad_perm:[2,3,0,1] row_mask:0xf bank_mask:0xf bound_ctrl:1
	v_add_f32_dpp v82, v82, v82 quad_perm:[2,3,0,1] row_mask:0xf bank_mask:0xf bound_ctrl:1
	v_add_f32_dpp v84, v84, v84 quad_perm:[2,3,0,1] row_mask:0xf bank_mask:0xf bound_ctrl:1
	v_add_f32_dpp v79, v79, v79 quad_perm:[2,3,0,1] row_mask:0xf bank_mask:0xf bound_ctrl:1
	v_add_f32_dpp v81, v81, v81 quad_perm:[2,3,0,1] row_mask:0xf bank_mask:0xf bound_ctrl:1
	v_add_f32_dpp v83, v83, v83 quad_perm:[2,3,0,1] row_mask:0xf bank_mask:0xf bound_ctrl:1
	v_add_f32_dpp v85, v85, v85 quad_perm:[2,3,0,1] row_mask:0xf bank_mask:0xf bound_ctrl:1
	v_add_u32_e32 v72, 0, v57
	v_ashrrev_i32_e32 v73, 31, v72
	v_lshlrev_b64 v[72:73], 10, v[72:73]
	v_lshl_add_u64 v[72:73], v[64:65], 0, v[72:73]
	v_cndmask_b32_e64 v154, v84, v82, s[16:17]
	v_cndmask_b32_e64 v155, v85, v83, s[16:17]
	v_cndmask_b32_e64 v154, v154, v80, s[14:15]
	v_cndmask_b32_e64 v155, v155, v81, s[14:15]
	v_cndmask_b32_e64 v154, v154, v78, s[12:13]
	v_cndmask_b32_e64 v155, v155, v79, s[12:13]
	v_cvt_pk_bf16_f32 v154, v154, v155
	global_store_dword v[72:73], v154, off
	v_pk_mul_f32 v[110:111], v[66:67], v[160:161] op_sel_hi:[1,0]
	v_pk_mul_f32 v[150:151], v[66:67], v[192:193] op_sel_hi:[1,0]
	v_pk_fma_f32 v[142:143], v[66:67], v[184:185], v[66:67] op_sel_hi:[1,0,1] neg_lo:[1,0,0] neg_hi:[1,0,0]
	v_pk_fma_f32 v[110:111], v[20:21], v[160:161], v[110:111] op_sel:[0,1,0]
	v_pk_fma_f32 v[150:151], v[20:21], v[192:193], v[150:151] op_sel:[0,1,0]
	v_pk_fma_f32 v[144:145], v[20:21], v[184:185], v[20:21] op_sel:[0,1,0] neg_lo:[1,0,0] neg_hi:[1,0,0]
	v_pk_fma_f32 v[110:111], v[68:69], v[162:163], v[110:111] op_sel_hi:[1,0,1]
	v_pk_fma_f32 v[150:151], v[68:69], v[194:195], v[150:151] op_sel_hi:[1,0,1]
	v_pk_fma_f32 v[146:147], v[68:69], v[186:187], v[68:69] op_sel_hi:[1,0,1] neg_lo:[1,0,0] neg_hi:[1,0,0]
	v_pk_fma_f32 v[110:111], v[70:71], v[162:163], v[110:111] op_sel:[0,1,0]
	v_pk_fma_f32 v[150:151], v[70:71], v[194:195], v[150:151] op_sel:[0,1,0]
	v_pk_fma_f32 v[148:149], v[70:71], v[186:187], v[70:71] op_sel:[0,1,0] neg_lo:[1,0,0] neg_hi:[1,0,0]
	v_pk_fma_f32 v[142:143], v[250:251], v[188:189], v[142:143] op_sel_hi:[1,0,1]
	v_pk_fma_f32 v[144:145], v[250:251], v[188:189], v[144:145] op_sel:[0,1,0]
	v_add_f32_dpp v150, v150, v150 quad_perm:[1,0,3,2] row_mask:0xf bank_mask:0xf bound_ctrl:1
	v_add_f32_dpp v151, v151, v151 quad_perm:[1,0,3,2] row_mask:0xf bank_mask:0xf bound_ctrl:1
	v_pk_fma_f32 v[146:147], v[250:251], v[190:191], v[146:147] op_sel_hi:[1,0,1]
	v_add_f32_dpp v150, v150, v150 quad_perm:[2,3,0,1] row_mask:0xf bank_mask:0xf bound_ctrl:1
	v_add_f32_dpp v151, v151, v151 quad_perm:[2,3,0,1] row_mask:0xf bank_mask:0xf bound_ctrl:1
	v_pk_fma_f32 v[148:149], v[250:251], v[190:191], v[148:149] op_sel:[0,1,0]
	v_add_f32_dpp v150, v150, v150 row_half_mirror row_mask:0xf bank_mask:0xf bound_ctrl:1
	v_add_f32_dpp v151, v151, v151 row_half_mirror row_mask:0xf bank_mask:0xf bound_ctrl:1
	s_nop 0
	s_waitcnt lgkmcnt(0)
; #define LAS __attribute__((address_space(3)))
; #define ROW16_SUM4(x, y, z, w) do { DPP4(x, y, z, w, "quad_perm:[1,0,3,2]", "s_nop 1"); DPP4(x, y, z, w, "quad_perm:[2,3,0,1]", ""); DPP4(x, y, z, w, "row_half_mirror", ""); DPP4(x, y, z, w, "row_mirror", ""); } while (0)
; template <bool SAMPLE>
; __device__ __forceinline__ void rwkv_unit(PR P, LAS float* lds, const int b, const int h, const int half, const int wv) {
;     ...
;                 for (int tt = 0; tt < GS; ++tt) {
;                     const LAS float* qn = q0 + (tt + 1 < GS ? tt + 1 : tt) * 384;
;                     const f32x4 nr4 = *(const LAS f32x4*)(qn + j0), no4 = *(const LAS f32x4*)(qn + 64 + j0), nk4 = *(const LAS f32x4*)(qn + 128 + j0), na4 = *(const LAS f32x4*)(qn + 192 + j0), nb4 = *(const LAS f32x4*)(qn + 256 + j0);
;                     const f32x2 nv2 = *(const LAS f32x2*)(qn + 320 + row0);
;                     f32x2 sa = (S[0] * a4[0] + S[1] * a4[1]) + (S[2] * a4[2] + S[3] * a4[3]);
;                     float sx = sa.x, sy = sa.y; ROW16_SUM4(sx, sy, py0, py1); sa = (f32x2){sx, sy};
;                     if (tt > 0) { yk0 = cgl == tt - 1 ? py0 : yk0; yk1 = cgl == tt - 1 ? py1 : yk1; }
; #pragma unroll
;                     for (int c = 0; c < 4; ++c) { f32x2 t = S[c] - S[c] * o4[c]; t = t + sa * b4[c]; S[c] = t + v2 * k4[c]; }
;                     const f32x2 y = (S[0] * r4[0] + S[1] * r4[1]) + (S[2] * r4[2] + S[3] * r4[3]);
;                     py0 = y.x; py1 = y.y;
;                     r4 = nr4; o4 = no4; k4 = nk4; a4 = na4; b4 = nb4; v2 = nv2;
	v_add_f32_dpp v150, v150, v150 row_mirror row_mask:0xf bank_mask:0xf bound_ctrl:1
	v_add_f32_dpp v151, v151, v151 row_mirror row_mask:0xf bank_mask:0xf bound_ctrl:1
	v_pk_fma_f32 v[66:67], v[150:151], v[196:197], v[142:143] op_sel_hi:[1,0,1]
	v_pk_fma_f32 v[20:21], v[150:151], v[196:197], v[144:145] op_sel:[0,1,0]
	v_pk_fma_f32 v[68:69], v[150:151], v[198:199], v[146:147] op_sel_hi:[1,0,1]
	v_pk_fma_f32 v[70:71], v[150:151], v[198:199], v[148:149] op_sel:[0,1,0]
	v_pk_mul_f32 v[112:113], v[66:67], v[180:181] op_sel_hi:[1,0]
	v_pk_mul_f32 v[150:151], v[66:67], v[212:213] op_sel_hi:[1,0]
	v_pk_fma_f32 v[142:143], v[66:67], v[204:205], v[66:67] op_sel_hi:[1,0,1] neg_lo:[1,0,0] neg_hi:[1,0,0]
	ds_read_b128 v[172:175], v152 offset:31488
	v_pk_fma_f32 v[112:113], v[20:21], v[180:181], v[112:113] op_sel:[0,1,0]
	v_pk_fma_f32 v[150:151], v[20:21], v[212:213], v[150:151] op_sel:[0,1,0]
	v_pk_fma_f32 v[144:145], v[20:21], v[204:205], v[20:21] op_sel:[0,1,0] neg_lo:[1,0,0] neg_hi:[1,0,0]
	ds_read_b128 v[164:167], v152 offset:30976
	v_pk_fma_f32 v[112:113], v[68:69], v[182:183], v[112:113] op_sel_hi:[1,0,1]
	v_pk_fma_f32 v[150:151], v[68:69], v[214:215], v[150:151] op_sel_hi:[1,0,1]
	v_pk_fma_f32 v[146:147], v[68:69], v[206:207], v[68:69] op_sel_hi:[1,0,1] neg_lo:[1,0,0] neg_hi:[1,0,0]
	ds_read2st64_b64 v[244:247], v153 offset0:62 offset1:65
	v_pk_fma_f32 v[112:113], v[70:71], v[182:183], v[112:113] op_sel:[0,1,0]
	v_pk_fma_f32 v[150:151], v[70:71], v[214:215], v[150:151] op_sel:[0,1,0]
	v_pk_fma_f32 v[148:149], v[70:71], v[206:207], v[70:71] op_sel:[0,1,0] neg_lo:[1,0,0] neg_hi:[1,0,0]
	ds_read_b128 v[168:171], v152 offset:31232
	v_pk_fma_f32 v[142:143], v[240:241], v[208:209], v[142:143] op_sel_hi:[1,0,1]
	v_pk_fma_f32 v[144:145], v[240:241], v[208:209], v[144:145] op_sel:[0,1,0]
	v_add_f32_dpp v150, v150, v150 quad_perm:[1,0,3,2] row_mask:0xf bank_mask:0xf bound_ctrl:1
	v_add_f32_dpp v151, v151, v151 quad_perm:[1,0,3,2] row_mask:0xf bank_mask:0xf bound_ctrl:1
	v_pk_fma_f32 v[146:147], v[240:241], v[210:211], v[146:147] op_sel_hi:[1,0,1]
	v_add_f32_dpp v150, v150, v150 quad_perm:[2,3,0,1] row_mask:0xf bank_mask:0xf bound_ctrl:1
	v_add_f32_dpp v151, v151, v151 quad_perm:[2,3,0,1] row_mask:0xf bank_mask:0xf bound_ctrl:1
	v_pk_fma_f32 v[148:149], v[240:241], v[210:211], v[148:149] op_sel:[0,1,0]
	v_add_f32_dpp v150, v150, v150 row_half_mirror row_mask:0xf bank_mask:0xf bound_ctrl:1
	v_add_f32_dpp v151, v151, v151 row_half_mirror row_mask:0xf bank_mask:0xf bound_ctrl:1
	ds_read_b128 v[192:195], v152 offset:33024
	v_add_f32_dpp v150, v150, v150 row_mirror row_mask:0xf bank_mask:0xf bound_ctrl:1
	v_add_f32_dpp v151, v151, v151 row_mirror row_mask:0xf bank_mask:0xf bound_ctrl:1
	ds_read_b128 v[184:187], v152 offset:32512
	ds_read_b128 v[176:179], v152 offset:31744
	ds_read_b128 v[188:191], v152 offset:32768
	ds_read_b128 v[196:199], v152 offset:33280
	ds_read_b128 v[160:163], v152 offset:30720
	ds_read_b128 v[180:183], v152 offset:32256
	v_pk_fma_f32 v[66:67], v[150:151], v[216:217], v[142:143] op_sel_hi:[1,0,1]
	v_pk_fma_f32 v[20:21], v[150:151], v[216:217], v[144:145] op_sel:[0,1,0]
	v_pk_fma_f32 v[68:69], v[150:151], v[218:219], v[146:147] op_sel_hi:[1,0,1]
	v_pk_fma_f32 v[70:71], v[150:151], v[218:219], v[148:149] op_sel:[0,1,0]
	v_pk_mul_f32 v[114:115], v[66:67], v[200:201] op_sel_hi:[1,0]
	v_pk_mul_f32 v[150:151], v[66:67], v[232:233] op_sel_hi:[1,0]
	v_pk_fma_f32 v[142:143], v[66:67], v[224:225], v[66:67] op_sel_hi:[1,0,1] neg_lo:[1,0,0] neg_hi:[1,0,0]
	v_pk_fma_f32 v[114:115], v[20:21], v[200:201], v[114:115] op_sel:[0,1,0]
	v_pk_fma_f32 v[150:151], v[20:21], v[232:233], v[150:151] op_sel:[0,1,0]
	v_pk_fma_f32 v[144:145], v[20:21], v[224:225], v[20:21] op_sel:[0,1,0] neg_lo:[1,0,0] neg_hi:[1,0,0]
	v_pk_fma_f32 v[114:115], v[68:69], v[202:203], v[114:115] op_sel_hi:[1,0,1]
	v_pk_fma_f32 v[150:151], v[68:69], v[234:235], v[150:151] op_sel_hi:[1,0,1]
	v_pk_fma_f32 v[146:147], v[68:69], v[226:227], v[68:69] op_sel_hi:[1,0,1] neg_lo:[1,0,0] neg_hi:[1,0,0]
	v_pk_fma_f32 v[114:115], v[70:71], v[202:203], v[114:115] op_sel:[0,1,0]
	v_pk_fma_f32 v[150:151], v[70:71], v[234:235], v[150:151] op_sel:[0,1,0]
	v_pk_fma_f32 v[148:149], v[70:71], v[226:227], v[70:71] op_sel:[0,1,0] neg_lo:[1,0,0] neg_hi:[1,0,0]
	v_pk_fma_f32 v[142:143], v[242:243], v[228:229], v[142:143] op_sel_hi:[1,0,1]
	v_pk_fma_f32 v[144:145], v[242:243], v[228:229], v[144:145] op_sel:[0,1,0]
	v_add_f32_dpp v150, v150, v150 quad_perm:[1,0,3,2] row_mask:0xf bank_mask:0xf bound_ctrl:1
	v_add_f32_dpp v151, v151, v151 quad_perm:[1,0,3,2] row_mask:0xf bank_mask:0xf bound_ctrl:1
	v_pk_fma_f32 v[146:147], v[242:243], v[230:231], v[146:147] op_sel_hi:[1,0,1]
	v_add_f32_dpp v150, v150, v150 quad_perm:[2,3,0,1] row_mask:0xf bank_mask:0xf bound_ctrl:1
	v_add_f32_dpp v151, v151, v151 quad_perm:[2,3,0,1] row_mask:0xf bank_mask:0xf bound_ctrl:1
	v_pk_fma_f32 v[148:149], v[242:243], v[230:231], v[148:149] op_sel:[0,1,0]
	v_add_f32_dpp v150, v150, v150 row_half_mirror row_mask:0xf bank_mask:0xf bound_ctrl:1
	v_add_f32_dpp v151, v151, v151 row_half_mirror row_mask:0xf bank_mask:0xf bound_ctrl:1
	s_nop 0
	s_waitcnt lgkmcnt(0)
; #define LAS __attribute__((address_space(3)))
; #define ROW16_SUM4(x, y, z, w) do { DPP4(x, y, z, w, "quad_perm:[1,0,3,2]", "s_nop 1"); DPP4(x, y, z, w, "quad_perm:[2,3,0,1]", ""); DPP4(x, y, z, w, "row_half_mirror", ""); DPP4(x, y, z, w, "row_mirror", ""); } while (0)
; template <bool SAMPLE>
; __device__ __forceinline__ void rwkv_unit(PR P, LAS float* lds, const int b, const int h, const int half, const int wv) {
;     ...
;                 for (int tt = 0; tt < GS; ++tt) {
;                     const LAS float* qn = q0 + (tt + 1 < GS ? tt + 1 : tt) * 384;
;                     const f32x4 nr4 = *(const LAS f32x4*)(qn + j0), no4 = *(const LAS f32x4*)(qn + 64 + j0), nk4 = *(const LAS f32x4*)(qn + 128 + j0), na4 = *(const LAS f32x4*)(qn + 192 + j0), nb4 = *(const LAS f32x4*)(qn + 256 + j0);
;                     const f32x2 nv2 = *(const LAS f32x2*)(qn + 320 + row0);
;                     f32x2 sa = (S[0] * a4[0] + S[1] * a4[1]) + (S[2] * a4[2] + S[3] * a4[3]);
;                     float sx = sa.x, sy = sa.y; ROW16_SUM4(sx, sy, py0, py1); sa = (f32x2){sx, sy};
;                     if (tt > 0) { yk0 = cgl == tt - 1 ? py0 : yk0; yk1 = cgl == tt - 1 ? py1 : yk1; }
; #pragma unroll
;                     for (int c = 0; c < 4; ++c) { f32x2 t = S[c] - S[c] * o4[c]; t = t + sa * b4[c]; S[c] = t + v2 * k4[c]; }
;                     const f32x2 y = (S[0] * r4[0] + S[1] * r4[1]) + (S[2] * r4[2] + S[3] * r4[3]);
;                     py0 = y.x; py1 = y.y;
;                     r4 = nr4; o4 = no4; k4 = nk4; a4 = na4; b4 = nb4; v2 = nv2;
	v_add_f32_dpp v150, v150, v150 row_mirror row_mask:0xf bank_mask:0xf bound_ctrl:1
	v_add_f32_dpp v151, v151, v151 row_mirror row_mask:0xf bank_mask:0xf bound_ctrl:1
	v_pk_fma_f32 v[66:67], v[150:151], v[236:237], v[142:143] op_sel_hi:[1,0,1]
	v_pk_fma_f32 v[20:21], v[150:151], v[236:237], v[144:145] op_sel:[0,1,0]
	v_pk_fma_f32 v[68:69], v[150:151], v[238:239], v[146:147] op_sel_hi:[1,0,1]
	v_pk_fma_f32 v[70:71], v[150:151], v[238:239], v[148:149] op_sel:[0,1,0]
	v_pk_mul_f32 v[116:117], v[66:67], v[220:221] op_sel_hi:[1,0]
	v_pk_mul_f32 v[150:151], v[66:67], v[172:173] op_sel_hi:[1,0]
	v_pk_fma_f32 v[142:143], v[66:67], v[164:165], v[66:67] op_sel_hi:[1,0,1] neg_lo:[1,0,0] neg_hi:[1,0,0]
	ds_read_b128 v[212:215], v152 offset:34560
	v_pk_fma_f32 v[116:117], v[20:21], v[220:221], v[116:117] op_sel:[0,1,0]
	v_pk_fma_f32 v[150:151], v[20:21], v[172:173], v[150:151] op_sel:[0,1,0]
	v_pk_fma_f32 v[144:145], v[20:21], v[164:165], v[20:21] op_sel:[0,1,0] neg_lo:[1,0,0] neg_hi:[1,0,0]
	ds_read_b128 v[204:207], v152 offset:34048
	v_pk_fma_f32 v[116:117], v[68:69], v[222:223], v[116:117] op_sel_hi:[1,0,1]
	v_pk_fma_f32 v[150:151], v[68:69], v[174:175], v[150:151] op_sel_hi:[1,0,1]
	v_pk_fma_f32 v[146:147], v[68:69], v[166:167], v[68:69] op_sel_hi:[1,0,1] neg_lo:[1,0,0] neg_hi:[1,0,0]
	ds_read2st64_b64 v[248:251], v153 offset0:68 offset1:71
	v_pk_fma_f32 v[116:117], v[70:71], v[222:223], v[116:117] op_sel:[0,1,0]
	v_pk_fma_f32 v[150:151], v[70:71], v[174:175], v[150:151] op_sel:[0,1,0]
	v_pk_fma_f32 v[148:149], v[70:71], v[166:167], v[70:71] op_sel:[0,1,0] neg_lo:[1,0,0] neg_hi:[1,0,0]
	ds_read_b128 v[208:211], v152 offset:34304
	v_pk_fma_f32 v[142:143], v[244:245], v[168:169], v[142:143] op_sel_hi:[1,0,1]
	v_pk_fma_f32 v[144:145], v[244:245], v[168:169], v[144:145] op_sel:[0,1,0]
	v_add_f32_dpp v150, v150, v150 quad_perm:[1,0,3,2] row_mask:0xf bank_mask:0xf bound_ctrl:1
	v_add_f32_dpp v151, v151, v151 quad_perm:[1,0,3,2] row_mask:0xf bank_mask:0xf bound_ctrl:1
	v_pk_fma_f32 v[146:147], v[244:245], v[170:171], v[146:147] op_sel_hi:[1,0,1]
	v_add_f32_dpp v150, v150, v150 quad_perm:[2,3,0,1] row_mask:0xf bank_mask:0xf bound_ctrl:1
	v_add_f32_dpp v151, v151, v151 quad_perm:[2,3,0,1] row_mask:0xf bank_mask:0xf bound_ctrl:1
	v_pk_fma_f32 v[148:149], v[244:245], v[170:171], v[148:149] op_sel:[0,1,0]
	v_add_f32_dpp v150, v150, v150 row_half_mirror row_mask:0xf bank_mask:0xf bound_ctrl:1
	v_add_f32_dpp v151, v151, v151 row_half_mirror row_mask:0xf bank_mask:0xf bound_ctrl:1
	ds_read_b128 v[232:235], v152 offset:36096
	v_add_f32_dpp v150, v150, v150 row_mirror row_mask:0xf bank_mask:0xf bound_ctrl:1
	v_add_f32_dpp v151, v151, v151 row_mirror row_mask:0xf bank_mask:0xf bound_ctrl:1
	ds_read_b128 v[224:227], v152 offset:35584
	ds_read_b128 v[216:219], v152 offset:34816
	ds_read_b128 v[228:231], v152 offset:35840
	ds_read_b128 v[236:239], v152 offset:36352
	ds_read_b128 v[200:203], v152 offset:33792
	ds_read_b128 v[220:223], v152 offset:35328
	v_pk_fma_f32 v[66:67], v[150:151], v[176:177], v[142:143] op_sel_hi:[1,0,1]
	v_pk_fma_f32 v[20:21], v[150:151], v[176:177], v[144:145] op_sel:[0,1,0]
	v_pk_fma_f32 v[68:69], v[150:151], v[178:179], v[146:147] op_sel_hi:[1,0,1]
	v_pk_fma_f32 v[70:71], v[150:151], v[178:179], v[148:149] op_sel:[0,1,0]
	v_pk_mul_f32 v[118:119], v[66:67], v[160:161] op_sel_hi:[1,0]
	v_pk_mul_f32 v[150:151], v[66:67], v[192:193] op_sel_hi:[1,0]
	v_pk_fma_f32 v[142:143], v[66:67], v[184:185], v[66:67] op_sel_hi:[1,0,1] neg_lo:[1,0,0] neg_hi:[1,0,0]
	v_pk_fma_f32 v[118:119], v[20:21], v[160:161], v[118:119] op_sel:[0,1,0]
	v_pk_fma_f32 v[150:151], v[20:21], v[192:193], v[150:151] op_sel:[0,1,0]
	v_pk_fma_f32 v[144:145], v[20:21], v[184:185], v[20:21] op_sel:[0,1,0] neg_lo:[1,0,0] neg_hi:[1,0,0]
	v_pk_fma_f32 v[118:119], v[68:69], v[162:163], v[118:119] op_sel_hi:[1,0,1]
	v_pk_fma_f32 v[150:151], v[68:69], v[194:195], v[150:151] op_sel_hi:[1,0,1]
	v_pk_fma_f32 v[146:147], v[68:69], v[186:187], v[68:69] op_sel_hi:[1,0,1] neg_lo:[1,0,0] neg_hi:[1,0,0]
	v_pk_fma_f32 v[118:119], v[70:71], v[162:163], v[118:119] op_sel:[0,1,0]
	v_pk_fma_f32 v[150:151], v[70:71], v[194:195], v[150:151] op_sel:[0,1,0]
	v_pk_fma_f32 v[148:149], v[70:71], v[186:187], v[70:71] op_sel:[0,1,0] neg_lo:[1,0,0] neg_hi:[1,0,0]
	v_pk_fma_f32 v[142:143], v[246:247], v[188:189], v[142:143] op_sel_hi:[1,0,1]
	v_pk_fma_f32 v[144:145], v[246:247], v[188:189], v[144:145] op_sel:[0,1,0]
	v_add_f32_dpp v150, v150, v150 quad_perm:[1,0,3,2] row_mask:0xf bank_mask:0xf bound_ctrl:1
	v_add_f32_dpp v151, v151, v151 quad_perm:[1,0,3,2] row_mask:0xf bank_mask:0xf bound_ctrl:1
	v_pk_fma_f32 v[146:147], v[246:247], v[190:191], v[146:147] op_sel_hi:[1,0,1]
	v_add_f32_dpp v150, v150, v150 quad_perm:[2,3,0,1] row_mask:0xf bank_mask:0xf bound_ctrl:1
	v_add_f32_dpp v151, v151, v151 quad_perm:[2,3,0,1] row_mask:0xf bank_mask:0xf bound_ctrl:1
	v_pk_fma_f32 v[148:149], v[246:247], v[190:191], v[148:149] op_sel:[0,1,0]
	v_add_f32_dpp v150, v150, v150 row_half_mirror row_mask:0xf bank_mask:0xf bound_ctrl:1
	v_add_f32_dpp v151, v151, v151 row_half_mirror row_mask:0xf bank_mask:0xf bound_ctrl:1
	s_nop 0
	s_waitcnt lgkmcnt(0)
; #define LAS __attribute__((address_space(3)))
; #define ROW16_SUM4(x, y, z, w) do { DPP4(x, y, z, w, "quad_perm:[1,0,3,2]", "s_nop 1"); DPP4(x, y, z, w, "quad_perm:[2,3,0,1]", ""); DPP4(x, y, z, w, "row_half_mirror", ""); DPP4(x, y, z, w, "row_mirror", ""); } while (0)
; template <bool SAMPLE>
; __device__ __forceinline__ void rwkv_unit(PR P, LAS float* lds, const int b, const int h, const int half, const int wv) {
;     ...
;                 for (int tt = 0; tt < GS; ++tt) {
;                     const LAS float* qn = q0 + (tt + 1 < GS ? tt + 1 : tt) * 384;
;                     const f32x4 nr4 = *(const LAS f32x4*)(qn + j0), no4 = *(const LAS f32x4*)(qn + 64 + j0), nk4 = *(const LAS f32x4*)(qn + 128 + j0), na4 = *(const LAS f32x4*)(qn + 192 + j0), nb4 = *(const LAS f32x4*)(qn + 256 + j0);
;                     const f32x2 nv2 = *(const LAS f32x2*)(qn + 320 + row0);
;                     f32x2 sa = (S[0] * a4[0] + S[1] * a4[1]) + (S[2] * a4[2] + S[3] * a4[3]);
;                     float sx = sa.x, sy = sa.y; ROW16_SUM4(sx, sy, py0, py1); sa = (f32x2){sx, sy};
;                     if (tt > 0) { yk0 = cgl == tt - 1 ? py0 : yk0; yk1 = cgl == tt - 1 ? py1 : yk1; }
; #pragma unroll
;                     for (int c = 0; c < 4; ++c) { f32x2 t = S[c] - S[c] * o4[c]; t = t + sa * b4[c]; S[c] = t + v2 * k4[c]; }
;                     const f32x2 y = (S[0] * r4[0] + S[1] * r4[1]) + (S[2] * r4[2] + S[3] * r4[3]);
;                     py0 = y.x; py1 = y.y;
;                     r4 = nr4; o4 = no4; k4 = nk4; a4 = na4; b4 = nb4; v2 = nv2;
	v_add_f32_dpp v150, v150, v150 row_mirror row_mask:0xf bank_mask:0xf bound_ctrl:1
	v_add_f32_dpp v151, v151, v151 row_mirror row_mask:0xf bank_mask:0xf bound_ctrl:1
	v_pk_fma_f32 v[66:67], v[150:151], v[196:197], v[142:143] op_sel_hi:[1,0,1]
	v_pk_fma_f32 v[20:21], v[150:151], v[196:197], v[144:145] op_sel:[0,1,0]
	v_pk_fma_f32 v[68:69], v[150:151], v[198:199], v[146:147] op_sel_hi:[1,0,1]
	v_pk_fma_f32 v[70:71], v[150:151], v[198:199], v[148:149] op_sel:[0,1,0]
	v_pk_mul_f32 v[120:121], v[66:67], v[180:181] op_sel_hi:[1,0]
	v_pk_mul_f32 v[150:151], v[66:67], v[212:213] op_sel_hi:[1,0]
	v_pk_fma_f32 v[142:143], v[66:67], v[204:205], v[66:67] op_sel_hi:[1,0,1] neg_lo:[1,0,0] neg_hi:[1,0,0]
	ds_read_b128 v[172:175], v152 offset:37632
	v_pk_fma_f32 v[120:121], v[20:21], v[180:181], v[120:121] op_sel:[0,1,0]
	v_pk_fma_f32 v[150:151], v[20:21], v[212:213], v[150:151] op_sel:[0,1,0]
	v_pk_fma_f32 v[144:145], v[20:21], v[204:205], v[20:21] op_sel:[0,1,0] neg_lo:[1,0,0] neg_hi:[1,0,0]
	ds_read_b128 v[164:167], v152 offset:37120
	v_pk_fma_f32 v[120:121], v[68:69], v[182:183], v[120:121] op_sel_hi:[1,0,1]
	v_pk_fma_f32 v[150:151], v[68:69], v[214:215], v[150:151] op_sel_hi:[1,0,1]
	v_pk_fma_f32 v[146:147], v[68:69], v[206:207], v[68:69] op_sel_hi:[1,0,1] neg_lo:[1,0,0] neg_hi:[1,0,0]
	ds_read2st64_b64 v[240:243], v153 offset0:74 offset1:77
	v_pk_fma_f32 v[120:121], v[70:71], v[182:183], v[120:121] op_sel:[0,1,0]
	v_pk_fma_f32 v[150:151], v[70:71], v[214:215], v[150:151] op_sel:[0,1,0]
	v_pk_fma_f32 v[148:149], v[70:71], v[206:207], v[70:71] op_sel:[0,1,0] neg_lo:[1,0,0] neg_hi:[1,0,0]
	ds_read_b128 v[168:171], v152 offset:37376
	v_pk_fma_f32 v[142:143], v[248:249], v[208:209], v[142:143] op_sel_hi:[1,0,1]
	v_pk_fma_f32 v[144:145], v[248:249], v[208:209], v[144:145] op_sel:[0,1,0]
	v_add_f32_dpp v150, v150, v150 quad_perm:[1,0,3,2] row_mask:0xf bank_mask:0xf bound_ctrl:1
	v_add_f32_dpp v151, v151, v151 quad_perm:[1,0,3,2] row_mask:0xf bank_mask:0xf bound_ctrl:1
	v_pk_fma_f32 v[146:147], v[248:249], v[210:211], v[146:147] op_sel_hi:[1,0,1]
	v_add_f32_dpp v150, v150, v150 quad_perm:[2,3,0,1] row_mask:0xf bank_mask:0xf bound_ctrl:1
	v_add_f32_dpp v151, v151, v151 quad_perm:[2,3,0,1] row_mask:0xf bank_mask:0xf bound_ctrl:1
	v_pk_fma_f32 v[148:149], v[248:249], v[210:211], v[148:149] op_sel:[0,1,0]
	v_add_f32_dpp v150, v150, v150 row_half_mirror row_mask:0xf bank_mask:0xf bound_ctrl:1
	v_add_f32_dpp v151, v151, v151 row_half_mirror row_mask:0xf bank_mask:0xf bound_ctrl:1
	ds_read_b128 v[192:195], v152 offset:39168
	v_add_f32_dpp v150, v150, v150 row_mirror row_mask:0xf bank_mask:0xf bound_ctrl:1
	v_add_f32_dpp v151, v151, v151 row_mirror row_mask:0xf bank_mask:0xf bound_ctrl:1
	ds_read_b128 v[184:187], v152 offset:38656
	ds_read_b128 v[176:179], v152 offset:37888
	ds_read_b128 v[188:191], v152 offset:38912
	ds_read_b128 v[196:199], v152 offset:39424
	ds_read_b128 v[160:163], v152 offset:36864
	ds_read_b128 v[180:183], v152 offset:38400
	v_pk_fma_f32 v[66:67], v[150:151], v[216:217], v[142:143] op_sel_hi:[1,0,1]
	v_pk_fma_f32 v[20:21], v[150:151], v[216:217], v[144:145] op_sel:[0,1,0]
	v_pk_fma_f32 v[68:69], v[150:151], v[218:219], v[146:147] op_sel_hi:[1,0,1]
	v_pk_fma_f32 v[70:71], v[150:151], v[218:219], v[148:149] op_sel:[0,1,0]
	v_pk_mul_f32 v[122:123], v[66:67], v[200:201] op_sel_hi:[1,0]
	v_pk_mul_f32 v[150:151], v[66:67], v[232:233] op_sel_hi:[1,0]
	v_pk_fma_f32 v[142:143], v[66:67], v[224:225], v[66:67] op_sel_hi:[1,0,1] neg_lo:[1,0,0] neg_hi:[1,0,0]
	v_pk_fma_f32 v[122:123], v[20:21], v[200:201], v[122:123] op_sel:[0,1,0]
	v_pk_fma_f32 v[150:151], v[20:21], v[232:233], v[150:151] op_sel:[0,1,0]
	v_pk_fma_f32 v[144:145], v[20:21], v[224:225], v[20:21] op_sel:[0,1,0] neg_lo:[1,0,0] neg_hi:[1,0,0]
	v_pk_fma_f32 v[122:123], v[68:69], v[202:203], v[122:123] op_sel_hi:[1,0,1]
	v_pk_fma_f32 v[150:151], v[68:69], v[234:235], v[150:151] op_sel_hi:[1,0,1]
	v_pk_fma_f32 v[146:147], v[68:69], v[226:227], v[68:69] op_sel_hi:[1,0,1] neg_lo:[1,0,0] neg_hi:[1,0,0]
	v_pk_fma_f32 v[122:123], v[70:71], v[202:203], v[122:123] op_sel:[0,1,0]
	v_pk_fma_f32 v[150:151], v[70:71], v[234:235], v[150:151] op_sel:[0,1,0]
	v_pk_fma_f32 v[148:149], v[70:71], v[226:227], v[70:71] op_sel:[0,1,0] neg_lo:[1,0,0] neg_hi:[1,0,0]
	v_pk_fma_f32 v[142:143], v[250:251], v[228:229], v[142:143] op_sel_hi:[1,0,1]
	v_pk_fma_f32 v[144:145], v[250:251], v[228:229], v[144:145] op_sel:[0,1,0]
	v_add_f32_dpp v150, v150, v150 quad_perm:[1,0,3,2] row_mask:0xf bank_mask:0xf bound_ctrl:1
	v_add_f32_dpp v151, v151, v151 quad_perm:[1,0,3,2] row_mask:0xf bank_mask:0xf bound_ctrl:1
	v_pk_fma_f32 v[146:147], v[250:251], v[230:231], v[146:147] op_sel_hi:[1,0,1]
	v_add_f32_dpp v150, v150, v150 quad_perm:[2,3,0,1] row_mask:0xf bank_mask:0xf bound_ctrl:1
	v_add_f32_dpp v151, v151, v151 quad_perm:[2,3,0,1] row_mask:0xf bank_mask:0xf bound_ctrl:1
	v_pk_fma_f32 v[148:149], v[250:251], v[230:231], v[148:149] op_sel:[0,1,0]
	v_add_f32_dpp v150, v150, v150 row_half_mirror row_mask:0xf bank_mask:0xf bound_ctrl:1
	v_add_f32_dpp v151, v151, v151 row_half_mirror row_mask:0xf bank_mask:0xf bound_ctrl:1
	s_nop 0
	s_waitcnt lgkmcnt(0)
; #define LAS __attribute__((address_space(3)))
; #define ROW16_SUM4(x, y, z, w) do { DPP4(x, y, z, w, "quad_perm:[1,0,3,2]", "s_nop 1"); DPP4(x, y, z, w, "quad_perm:[2,3,0,1]", ""); DPP4(x, y, z, w, "row_half_mirror", ""); DPP4(x, y, z, w, "row_mirror", ""); } while (0)
; template <bool SAMPLE>
; __device__ __forceinline__ void rwkv_unit(PR P, LAS float* lds, const int b, const int h, const int half, const int wv) {
;     ...
;                 for (int tt = 0; tt < GS; ++tt) {
;                     const LAS float* qn = q0 + (tt + 1 < GS ? tt + 1 : tt) * 384;
;                     const f32x4 nr4 = *(const LAS f32x4*)(qn + j0), no4 = *(const LAS f32x4*)(qn + 64 + j0), nk4 = *(const LAS f32x4*)(qn + 128 + j0), na4 = *(const LAS f32x4*)(qn + 192 + j0), nb4 = *(const LAS f32x4*)(qn + 256 + j0);
;                     const f32x2 nv2 = *(const LAS f32x2*)(qn + 320 + row0);
;                     f32x2 sa = (S[0] * a4[0] + S[1] * a4[1]) + (S[2] * a4[2] + S[3] * a4[3]);
;                     float sx = sa.x, sy = sa.y; ROW16_SUM4(sx, sy, py0, py1); sa = (f32x2){sx, sy};
;                     if (tt > 0) { yk0 = cgl == tt - 1 ? py0 : yk0; yk1 = cgl == tt - 1 ? py1 : yk1; }
; #pragma unroll
;                     for (int c = 0; c < 4; ++c) { f32x2 t = S[c] - S[c] * o4[c]; t = t + sa * b4[c]; S[c] = t + v2 * k4[c]; }
;                     const f32x2 y = (S[0] * r4[0] + S[1] * r4[1]) + (S[2] * r4[2] + S[3] * r4[3]);
;                     py0 = y.x; py1 = y.y;
;                     r4 = nr4; o4 = no4; k4 = nk4; a4 = na4; b4 = nb4; v2 = nv2;
	v_add_f32_dpp v150, v150, v150 row_mirror row_mask:0xf bank_mask:0xf bound_ctrl:1
	v_add_f32_dpp v151, v151, v151 row_mirror row_mask:0xf bank_mask:0xf bound_ctrl:1
	v_pk_fma_f32 v[66:67], v[150:151], v[236:237], v[142:143] op_sel_hi:[1,0,1]
	v_pk_fma_f32 v[20:21], v[150:151], v[236:237], v[144:145] op_sel:[0,1,0]
	v_pk_fma_f32 v[68:69], v[150:151], v[238:239], v[146:147] op_sel_hi:[1,0,1]
	v_pk_fma_f32 v[70:71], v[150:151], v[238:239], v[148:149] op_sel:[0,1,0]
	v_pk_mul_f32 v[124:125], v[66:67], v[220:221] op_sel_hi:[1,0]
	v_pk_mul_f32 v[150:151], v[66:67], v[172:173] op_sel_hi:[1,0]
	v_pk_fma_f32 v[142:143], v[66:67], v[164:165], v[66:67] op_sel_hi:[1,0,1] neg_lo:[1,0,0] neg_hi:[1,0,0]
	ds_read_b128 v[212:215], v152 offset:40704
	v_pk_fma_f32 v[124:125], v[20:21], v[220:221], v[124:125] op_sel:[0,1,0]
	v_pk_fma_f32 v[150:151], v[20:21], v[172:173], v[150:151] op_sel:[0,1,0]
	v_pk_fma_f32 v[144:145], v[20:21], v[164:165], v[20:21] op_sel:[0,1,0] neg_lo:[1,0,0] neg_hi:[1,0,0]
	ds_read_b128 v[204:207], v152 offset:40192
	v_pk_fma_f32 v[124:125], v[68:69], v[222:223], v[124:125] op_sel_hi:[1,0,1]
	v_pk_fma_f32 v[150:151], v[68:69], v[174:175], v[150:151] op_sel_hi:[1,0,1]
	v_pk_fma_f32 v[146:147], v[68:69], v[166:167], v[68:69] op_sel_hi:[1,0,1] neg_lo:[1,0,0] neg_hi:[1,0,0]
	ds_read2st64_b64 v[244:247], v153 offset0:80 offset1:83
	v_pk_fma_f32 v[124:125], v[70:71], v[222:223], v[124:125] op_sel:[0,1,0]
	v_pk_fma_f32 v[150:151], v[70:71], v[174:175], v[150:151] op_sel:[0,1,0]
	v_pk_fma_f32 v[148:149], v[70:71], v[166:167], v[70:71] op_sel:[0,1,0] neg_lo:[1,0,0] neg_hi:[1,0,0]
	ds_read_b128 v[208:211], v152 offset:40448
	v_pk_fma_f32 v[142:143], v[240:241], v[168:169], v[142:143] op_sel_hi:[1,0,1]
	v_pk_fma_f32 v[144:145], v[240:241], v[168:169], v[144:145] op_sel:[0,1,0]
	v_add_f32_dpp v150, v150, v150 quad_perm:[1,0,3,2] row_mask:0xf bank_mask:0xf bound_ctrl:1
	v_add_f32_dpp v151, v151, v151 quad_perm:[1,0,3,2] row_mask:0xf bank_mask:0xf bound_ctrl:1
	v_pk_fma_f32 v[146:147], v[240:241], v[170:171], v[146:147] op_sel_hi:[1,0,1]
	v_add_f32_dpp v150, v150, v150 quad_perm:[2,3,0,1] row_mask:0xf bank_mask:0xf bound_ctrl:1
	v_add_f32_dpp v151, v151, v151 quad_perm:[2,3,0,1] row_mask:0xf bank_mask:0xf bound_ctrl:1
	v_pk_fma_f32 v[148:149], v[240:241], v[170:171], v[148:149] op_sel:[0,1,0]
	v_add_f32_dpp v150, v150, v150 row_half_mirror row_mask:0xf bank_mask:0xf bound_ctrl:1
	v_add_f32_dpp v151, v151, v151 row_half_mirror row_mask:0xf bank_mask:0xf bound_ctrl:1
	ds_read_b128 v[232:235], v152 offset:42240
	v_add_f32_dpp v150, v150, v150 row_mirror row_mask:0xf bank_mask:0xf bound_ctrl:1
	v_add_f32_dpp v151, v151, v151 row_mirror row_mask:0xf bank_mask:0xf bound_ctrl:1
	ds_read_b128 v[224:227], v152 offset:41728
	ds_read_b128 v[216:219], v152 offset:40960
	ds_read_b128 v[228:231], v152 offset:41984
	ds_read_b128 v[236:239], v152 offset:42496
	ds_read_b128 v[200:203], v152 offset:39936
	ds_read_b128 v[220:223], v152 offset:41472
	v_pk_fma_f32 v[66:67], v[150:151], v[176:177], v[142:143] op_sel_hi:[1,0,1]
	v_pk_fma_f32 v[20:21], v[150:151], v[176:177], v[144:145] op_sel:[0,1,0]
	v_pk_fma_f32 v[68:69], v[150:151], v[178:179], v[146:147] op_sel_hi:[1,0,1]
	v_pk_fma_f32 v[70:71], v[150:151], v[178:179], v[148:149] op_sel:[0,1,0]
	v_pk_mul_f32 v[126:127], v[66:67], v[160:161] op_sel_hi:[1,0]
	v_pk_mul_f32 v[150:151], v[66:67], v[192:193] op_sel_hi:[1,0]
	v_pk_fma_f32 v[142:143], v[66:67], v[184:185], v[66:67] op_sel_hi:[1,0,1] neg_lo:[1,0,0] neg_hi:[1,0,0]
	v_pk_fma_f32 v[126:127], v[20:21], v[160:161], v[126:127] op_sel:[0,1,0]
	v_pk_fma_f32 v[150:151], v[20:21], v[192:193], v[150:151] op_sel:[0,1,0]
	v_pk_fma_f32 v[144:145], v[20:21], v[184:185], v[20:21] op_sel:[0,1,0] neg_lo:[1,0,0] neg_hi:[1,0,0]
	v_pk_fma_f32 v[126:127], v[68:69], v[162:163], v[126:127] op_sel_hi:[1,0,1]
	v_pk_fma_f32 v[150:151], v[68:69], v[194:195], v[150:151] op_sel_hi:[1,0,1]
	v_pk_fma_f32 v[146:147], v[68:69], v[186:187], v[68:69] op_sel_hi:[1,0,1] neg_lo:[1,0,0] neg_hi:[1,0,0]
	v_pk_fma_f32 v[126:127], v[70:71], v[162:163], v[126:127] op_sel:[0,1,0]
	v_pk_fma_f32 v[150:151], v[70:71], v[194:195], v[150:151] op_sel:[0,1,0]
	v_pk_fma_f32 v[148:149], v[70:71], v[186:187], v[70:71] op_sel:[0,1,0] neg_lo:[1,0,0] neg_hi:[1,0,0]
	v_pk_fma_f32 v[142:143], v[242:243], v[188:189], v[142:143] op_sel_hi:[1,0,1]
	v_pk_fma_f32 v[144:145], v[242:243], v[188:189], v[144:145] op_sel:[0,1,0]
	v_add_f32_dpp v150, v150, v150 quad_perm:[1,0,3,2] row_mask:0xf bank_mask:0xf bound_ctrl:1
	v_add_f32_dpp v151, v151, v151 quad_perm:[1,0,3,2] row_mask:0xf bank_mask:0xf bound_ctrl:1
	v_pk_fma_f32 v[146:147], v[242:243], v[190:191], v[146:147] op_sel_hi:[1,0,1]
	v_add_f32_dpp v150, v150, v150 quad_perm:[2,3,0,1] row_mask:0xf bank_mask:0xf bound_ctrl:1
	v_add_f32_dpp v151, v151, v151 quad_perm:[2,3,0,1] row_mask:0xf bank_mask:0xf bound_ctrl:1
	v_pk_fma_f32 v[148:149], v[242:243], v[190:191], v[148:149] op_sel:[0,1,0]
	v_add_f32_dpp v150, v150, v150 row_half_mirror row_mask:0xf bank_mask:0xf bound_ctrl:1
	v_add_f32_dpp v151, v151, v151 row_half_mirror row_mask:0xf bank_mask:0xf bound_ctrl:1
	s_nop 0
	s_waitcnt lgkmcnt(0)
; #define LAS __attribute__((address_space(3)))
; #define ROW16_SUM4(x, y, z, w) do { DPP4(x, y, z, w, "quad_perm:[1,0,3,2]", "s_nop 1"); DPP4(x, y, z, w, "quad_perm:[2,3,0,1]", ""); DPP4(x, y, z, w, "row_half_mirror", ""); DPP4(x, y, z, w, "row_mirror", ""); } while (0)
; template <bool SAMPLE>
; __device__ __forceinline__ void rwkv_unit(PR P, LAS float* lds, const int b, const int h, const int half, const int wv) {
;     ...
;                 for (int tt = 0; tt < GS; ++tt) {
;                     const LAS float* qn = q0 + (tt + 1 < GS ? tt + 1 : tt) * 384;
;                     const f32x4 nr4 = *(const LAS f32x4*)(qn + j0), no4 = *(const LAS f32x4*)(qn + 64 + j0), nk4 = *(const LAS f32x4*)(qn + 128 + j0), na4 = *(const LAS f32x4*)(qn + 192 + j0), nb4 = *(const LAS f32x4*)(qn + 256 + j0);
;                     const f32x2 nv2 = *(const LAS f32x2*)(qn + 320 + row0);
;                     f32x2 sa = (S[0] * a4[0] + S[1] * a4[1]) + (S[2] * a4[2] + S[3] * a4[3]);
;                     float sx = sa.x, sy = sa.y; ROW16_SUM4(sx, sy, py0, py1); sa = (f32x2){sx, sy};
;                     if (tt > 0) { yk0 = cgl == tt - 1 ? py0 : yk0; yk1 = cgl == tt - 1 ? py1 : yk1; }
; #pragma unroll
;                     for (int c = 0; c < 4; ++c) { f32x2 t = S[c] - S[c] * o4[c]; t = t + sa * b4[c]; S[c] = t + v2 * k4[c]; }
;                     const f32x2 y = (S[0] * r4[0] + S[1] * r4[1]) + (S[2] * r4[2] + S[3] * r4[3]);
;                     py0 = y.x; py1 = y.y;
;                     r4 = nr4; o4 = no4; k4 = nk4; a4 = na4; b4 = nb4; v2 = nv2;
	v_add_f32_dpp v150, v150, v150 row_mirror row_mask:0xf bank_mask:0xf bound_ctrl:1
	v_add_f32_dpp v151, v151, v151 row_mirror row_mask:0xf bank_mask:0xf bound_ctrl:1
	v_pk_fma_f32 v[66:67], v[150:151], v[196:197], v[142:143] op_sel_hi:[1,0,1]
	v_pk_fma_f32 v[20:21], v[150:151], v[196:197], v[144:145] op_sel:[0,1,0]
	v_pk_fma_f32 v[68:69], v[150:151], v[198:199], v[146:147] op_sel_hi:[1,0,1]
	v_pk_fma_f32 v[70:71], v[150:151], v[198:199], v[148:149] op_sel:[0,1,0]
	v_pk_mul_f32 v[128:129], v[66:67], v[180:181] op_sel_hi:[1,0]
	v_pk_mul_f32 v[150:151], v[66:67], v[212:213] op_sel_hi:[1,0]
	v_pk_fma_f32 v[142:143], v[66:67], v[204:205], v[66:67] op_sel_hi:[1,0,1] neg_lo:[1,0,0] neg_hi:[1,0,0]
	ds_read_b128 v[172:175], v152 offset:43776
	v_pk_fma_f32 v[128:129], v[20:21], v[180:181], v[128:129] op_sel:[0,1,0]
	v_pk_fma_f32 v[150:151], v[20:21], v[212:213], v[150:151] op_sel:[0,1,0]
	v_pk_fma_f32 v[144:145], v[20:21], v[204:205], v[20:21] op_sel:[0,1,0] neg_lo:[1,0,0] neg_hi:[1,0,0]
	ds_read_b128 v[164:167], v152 offset:43264
	v_pk_fma_f32 v[128:129], v[68:69], v[182:183], v[128:129] op_sel_hi:[1,0,1]
	v_pk_fma_f32 v[150:151], v[68:69], v[214:215], v[150:151] op_sel_hi:[1,0,1]
	v_pk_fma_f32 v[146:147], v[68:69], v[206:207], v[68:69] op_sel_hi:[1,0,1] neg_lo:[1,0,0] neg_hi:[1,0,0]
	ds_read2st64_b64 v[248:251], v153 offset0:86 offset1:89
	v_pk_fma_f32 v[128:129], v[70:71], v[182:183], v[128:129] op_sel:[0,1,0]
	v_pk_fma_f32 v[150:151], v[70:71], v[214:215], v[150:151] op_sel:[0,1,0]
	v_pk_fma_f32 v[148:149], v[70:71], v[206:207], v[70:71] op_sel:[0,1,0] neg_lo:[1,0,0] neg_hi:[1,0,0]
	ds_read_b128 v[168:171], v152 offset:43520
	v_pk_fma_f32 v[142:143], v[244:245], v[208:209], v[142:143] op_sel_hi:[1,0,1]
	v_pk_fma_f32 v[144:145], v[244:245], v[208:209], v[144:145] op_sel:[0,1,0]
	v_add_f32_dpp v150, v150, v150 quad_perm:[1,0,3,2] row_mask:0xf bank_mask:0xf bound_ctrl:1
	v_add_f32_dpp v151, v151, v151 quad_perm:[1,0,3,2] row_mask:0xf bank_mask:0xf bound_ctrl:1
	v_pk_fma_f32 v[146:147], v[244:245], v[210:211], v[146:147] op_sel_hi:[1,0,1]
	v_add_f32_dpp v150, v150, v150 quad_perm:[2,3,0,1] row_mask:0xf bank_mask:0xf bound_ctrl:1
	v_add_f32_dpp v151, v151, v151 quad_perm:[2,3,0,1] row_mask:0xf bank_mask:0xf bound_ctrl:1
	v_pk_fma_f32 v[148:149], v[244:245], v[210:211], v[148:149] op_sel:[0,1,0]
	v_add_f32_dpp v150, v150, v150 row_half_mirror row_mask:0xf bank_mask:0xf bound_ctrl:1
	v_add_f32_dpp v151, v151, v151 row_half_mirror row_mask:0xf bank_mask:0xf bound_ctrl:1
	ds_read_b128 v[192:195], v152 offset:45312
	v_add_f32_dpp v150, v150, v150 row_mirror row_mask:0xf bank_mask:0xf bound_ctrl:1
	v_add_f32_dpp v151, v151, v151 row_mirror row_mask:0xf bank_mask:0xf bound_ctrl:1
	ds_read_b128 v[184:187], v152 offset:44800
	ds_read_b128 v[176:179], v152 offset:44032
	ds_read_b128 v[188:191], v152 offset:45056
	ds_read_b128 v[196:199], v152 offset:45568
	ds_read_b128 v[160:163], v152 offset:43008
	ds_read_b128 v[180:183], v152 offset:44544
	v_pk_fma_f32 v[66:67], v[150:151], v[216:217], v[142:143] op_sel_hi:[1,0,1]
	v_pk_fma_f32 v[20:21], v[150:151], v[216:217], v[144:145] op_sel:[0,1,0]
	v_pk_fma_f32 v[68:69], v[150:151], v[218:219], v[146:147] op_sel_hi:[1,0,1]
	v_pk_fma_f32 v[70:71], v[150:151], v[218:219], v[148:149] op_sel:[0,1,0]
	v_pk_mul_f32 v[130:131], v[66:67], v[200:201] op_sel_hi:[1,0]
	v_pk_mul_f32 v[150:151], v[66:67], v[232:233] op_sel_hi:[1,0]
	v_pk_fma_f32 v[142:143], v[66:67], v[224:225], v[66:67] op_sel_hi:[1,0,1] neg_lo:[1,0,0] neg_hi:[1,0,0]
	v_pk_fma_f32 v[130:131], v[20:21], v[200:201], v[130:131] op_sel:[0,1,0]
	v_pk_fma_f32 v[150:151], v[20:21], v[232:233], v[150:151] op_sel:[0,1,0]
	v_pk_fma_f32 v[144:145], v[20:21], v[224:225], v[20:21] op_sel:[0,1,0] neg_lo:[1,0,0] neg_hi:[1,0,0]
	v_pk_fma_f32 v[130:131], v[68:69], v[202:203], v[130:131] op_sel_hi:[1,0,1]
	v_pk_fma_f32 v[150:151], v[68:69], v[234:235], v[150:151] op_sel_hi:[1,0,1]
	v_pk_fma_f32 v[146:147], v[68:69], v[226:227], v[68:69] op_sel_hi:[1,0,1] neg_lo:[1,0,0] neg_hi:[1,0,0]
	v_pk_fma_f32 v[130:131], v[70:71], v[202:203], v[130:131] op_sel:[0,1,0]
	v_pk_fma_f32 v[150:151], v[70:71], v[234:235], v[150:151] op_sel:[0,1,0]
	v_pk_fma_f32 v[148:149], v[70:71], v[226:227], v[70:71] op_sel:[0,1,0] neg_lo:[1,0,0] neg_hi:[1,0,0]
	v_pk_fma_f32 v[142:143], v[246:247], v[228:229], v[142:143] op_sel_hi:[1,0,1]
	v_pk_fma_f32 v[144:145], v[246:247], v[228:229], v[144:145] op_sel:[0,1,0]
	v_add_f32_dpp v150, v150, v150 quad_perm:[1,0,3,2] row_mask:0xf bank_mask:0xf bound_ctrl:1
	v_add_f32_dpp v151, v151, v151 quad_perm:[1,0,3,2] row_mask:0xf bank_mask:0xf bound_ctrl:1
	v_pk_fma_f32 v[146:147], v[246:247], v[230:231], v[146:147] op_sel_hi:[1,0,1]
	v_add_f32_dpp v150, v150, v150 quad_perm:[2,3,0,1] row_mask:0xf bank_mask:0xf bound_ctrl:1
	v_add_f32_dpp v151, v151, v151 quad_perm:[2,3,0,1] row_mask:0xf bank_mask:0xf bound_ctrl:1
	v_pk_fma_f32 v[148:149], v[246:247], v[230:231], v[148:149] op_sel:[0,1,0]
	v_add_f32_dpp v150, v150, v150 row_half_mirror row_mask:0xf bank_mask:0xf bound_ctrl:1
	v_add_f32_dpp v151, v151, v151 row_half_mirror row_mask:0xf bank_mask:0xf bound_ctrl:1
	s_nop 0
	s_waitcnt lgkmcnt(0)
; #define LAS __attribute__((address_space(3)))
; #define ROW16_SUM4(x, y, z, w) do { DPP4(x, y, z, w, "quad_perm:[1,0,3,2]", "s_nop 1"); DPP4(x, y, z, w, "quad_perm:[2,3,0,1]", ""); DPP4(x, y, z, w, "row_half_mirror", ""); DPP4(x, y, z, w, "row_mirror", ""); } while (0)
; template <bool SAMPLE>
; __device__ __forceinline__ void rwkv_unit(PR P, LAS float* lds, const int b, const int h, const int half, const int wv) {
;     ...
;                 for (int tt = 0; tt < GS; ++tt) {
;                     const LAS float* qn = q0 + (tt + 1 < GS ? tt + 1 : tt) * 384;
;                     const f32x4 nr4 = *(const LAS f32x4*)(qn + j0), no4 = *(const LAS f32x4*)(qn + 64 + j0), nk4 = *(const LAS f32x4*)(qn + 128 + j0), na4 = *(const LAS f32x4*)(qn + 192 + j0), nb4 = *(const LAS f32x4*)(qn + 256 + j0);
;                     const f32x2 nv2 = *(const LAS f32x2*)(qn + 320 + row0);
;                     f32x2 sa = (S[0] * a4[0] + S[1] * a4[1]) + (S[2] * a4[2] + S[3] * a4[3]);
;                     float sx = sa.x, sy = sa.y; ROW16_SUM4(sx, sy, py0, py1); sa = (f32x2){sx, sy};
;                     if (tt > 0) { yk0 = cgl == tt - 1 ? py0 : yk0; yk1 = cgl == tt - 1 ? py1 : yk1; }
; #pragma unroll
;                     for (int c = 0; c < 4; ++c) { f32x2 t = S[c] - S[c] * o4[c]; t = t + sa * b4[c]; S[c] = t + v2 * k4[c]; }
;                     const f32x2 y = (S[0] * r4[0] + S[1] * r4[1]) + (S[2] * r4[2] + S[3] * r4[3]);
;                     py0 = y.x; py1 = y.y;
;                     r4 = nr4; o4 = no4; k4 = nk4; a4 = na4; b4 = nb4; v2 = nv2;
	v_add_f32_dpp v150, v150, v150 row_mirror row_mask:0xf bank_mask:0xf bound_ctrl:1
	v_add_f32_dpp v151, v151, v151 row_mirror row_mask:0xf bank_mask:0xf bound_ctrl:1
	v_pk_fma_f32 v[66:67], v[150:151], v[236:237], v[142:143] op_sel_hi:[1,0,1]
	v_pk_fma_f32 v[20:21], v[150:151], v[236:237], v[144:145] op_sel:[0,1,0]
	v_pk_fma_f32 v[68:69], v[150:151], v[238:239], v[146:147] op_sel_hi:[1,0,1]
	v_pk_fma_f32 v[70:71], v[150:151], v[238:239], v[148:149] op_sel:[0,1,0]
	v_pk_mul_f32 v[132:133], v[66:67], v[220:221] op_sel_hi:[1,0]
	v_pk_mul_f32 v[150:151], v[66:67], v[172:173] op_sel_hi:[1,0]
	v_pk_fma_f32 v[142:143], v[66:67], v[164:165], v[66:67] op_sel_hi:[1,0,1] neg_lo:[1,0,0] neg_hi:[1,0,0]
	ds_read_b128 v[212:215], v152 offset:46848
	v_pk_fma_f32 v[132:133], v[20:21], v[220:221], v[132:133] op_sel:[0,1,0]
	v_pk_fma_f32 v[150:151], v[20:21], v[172:173], v[150:151] op_sel:[0,1,0]
	v_pk_fma_f32 v[144:145], v[20:21], v[164:165], v[20:21] op_sel:[0,1,0] neg_lo:[1,0,0] neg_hi:[1,0,0]
	ds_read_b128 v[204:207], v152 offset:46336
	v_pk_fma_f32 v[132:133], v[68:69], v[222:223], v[132:133] op_sel_hi:[1,0,1]
	v_pk_fma_f32 v[150:151], v[68:69], v[174:175], v[150:151] op_sel_hi:[1,0,1]
	v_pk_fma_f32 v[146:147], v[68:69], v[166:167], v[68:69] op_sel_hi:[1,0,1] neg_lo:[1,0,0] neg_hi:[1,0,0]
	ds_read2st64_b64 v[240:243], v153 offset0:92 offset1:95
	v_pk_fma_f32 v[132:133], v[70:71], v[222:223], v[132:133] op_sel:[0,1,0]
	v_pk_fma_f32 v[150:151], v[70:71], v[174:175], v[150:151] op_sel:[0,1,0]
	v_pk_fma_f32 v[148:149], v[70:71], v[166:167], v[70:71] op_sel:[0,1,0] neg_lo:[1,0,0] neg_hi:[1,0,0]
	ds_read_b128 v[208:211], v152 offset:46592
	v_pk_fma_f32 v[142:143], v[248:249], v[168:169], v[142:143] op_sel_hi:[1,0,1]
	v_pk_fma_f32 v[144:145], v[248:249], v[168:169], v[144:145] op_sel:[0,1,0]
	v_add_f32_dpp v150, v150, v150 quad_perm:[1,0,3,2] row_mask:0xf bank_mask:0xf bound_ctrl:1
	v_add_f32_dpp v151, v151, v151 quad_perm:[1,0,3,2] row_mask:0xf bank_mask:0xf bound_ctrl:1
	v_pk_fma_f32 v[146:147], v[248:249], v[170:171], v[146:147] op_sel_hi:[1,0,1]
	v_add_f32_dpp v150, v150, v150 quad_perm:[2,3,0,1] row_mask:0xf bank_mask:0xf bound_ctrl:1
	v_add_f32_dpp v151, v151, v151 quad_perm:[2,3,0,1] row_mask:0xf bank_mask:0xf bound_ctrl:1
	v_pk_fma_f32 v[148:149], v[248:249], v[170:171], v[148:149] op_sel:[0,1,0]
	v_add_f32_dpp v150, v150, v150 row_half_mirror row_mask:0xf bank_mask:0xf bound_ctrl:1
	v_add_f32_dpp v151, v151, v151 row_half_mirror row_mask:0xf bank_mask:0xf bound_ctrl:1
	ds_read_b128 v[232:235], v152 offset:48384
	v_add_f32_dpp v150, v150, v150 row_mirror row_mask:0xf bank_mask:0xf bound_ctrl:1
	v_add_f32_dpp v151, v151, v151 row_mirror row_mask:0xf bank_mask:0xf bound_ctrl:1
	ds_read_b128 v[224:227], v152 offset:47872
	ds_read_b128 v[216:219], v152 offset:47104
	ds_read_b128 v[228:231], v152 offset:48128
	ds_read_b128 v[236:239], v152 offset:48640
	ds_read_b128 v[200:203], v152 offset:46080
	ds_read_b128 v[220:223], v152 offset:47616
	v_pk_fma_f32 v[66:67], v[150:151], v[176:177], v[142:143] op_sel_hi:[1,0,1]
	v_pk_fma_f32 v[20:21], v[150:151], v[176:177], v[144:145] op_sel:[0,1,0]
	v_pk_fma_f32 v[68:69], v[150:151], v[178:179], v[146:147] op_sel_hi:[1,0,1]
	v_pk_fma_f32 v[70:71], v[150:151], v[178:179], v[148:149] op_sel:[0,1,0]
	v_pk_mul_f32 v[134:135], v[66:67], v[160:161] op_sel_hi:[1,0]
	v_pk_mul_f32 v[150:151], v[66:67], v[192:193] op_sel_hi:[1,0]
	v_pk_fma_f32 v[142:143], v[66:67], v[184:185], v[66:67] op_sel_hi:[1,0,1] neg_lo:[1,0,0] neg_hi:[1,0,0]
	v_pk_fma_f32 v[134:135], v[20:21], v[160:161], v[134:135] op_sel:[0,1,0]
	v_pk_fma_f32 v[150:151], v[20:21], v[192:193], v[150:151] op_sel:[0,1,0]
	v_pk_fma_f32 v[144:145], v[20:21], v[184:185], v[20:21] op_sel:[0,1,0] neg_lo:[1,0,0] neg_hi:[1,0,0]
	v_pk_fma_f32 v[134:135], v[68:69], v[162:163], v[134:135] op_sel_hi:[1,0,1]
	v_pk_fma_f32 v[150:151], v[68:69], v[194:195], v[150:151] op_sel_hi:[1,0,1]
	v_pk_fma_f32 v[146:147], v[68:69], v[186:187], v[68:69] op_sel_hi:[1,0,1] neg_lo:[1,0,0] neg_hi:[1,0,0]
	v_pk_fma_f32 v[134:135], v[70:71], v[162:163], v[134:135] op_sel:[0,1,0]
	v_pk_fma_f32 v[150:151], v[70:71], v[194:195], v[150:151] op_sel:[0,1,0]
	v_pk_fma_f32 v[148:149], v[70:71], v[186:187], v[70:71] op_sel:[0,1,0] neg_lo:[1,0,0] neg_hi:[1,0,0]
	v_pk_fma_f32 v[142:143], v[250:251], v[188:189], v[142:143] op_sel_hi:[1,0,1]
	v_pk_fma_f32 v[144:145], v[250:251], v[188:189], v[144:145] op_sel:[0,1,0]
	v_add_f32_dpp v150, v150, v150 quad_perm:[1,0,3,2] row_mask:0xf bank_mask:0xf bound_ctrl:1
	v_add_f32_dpp v151, v151, v151 quad_perm:[1,0,3,2] row_mask:0xf bank_mask:0xf bound_ctrl:1
	v_pk_fma_f32 v[146:147], v[250:251], v[190:191], v[146:147] op_sel_hi:[1,0,1]
	v_add_f32_dpp v150, v150, v150 quad_perm:[2,3,0,1] row_mask:0xf bank_mask:0xf bound_ctrl:1
	v_add_f32_dpp v151, v151, v151 quad_perm:[2,3,0,1] row_mask:0xf bank_mask:0xf bound_ctrl:1
	v_pk_fma_f32 v[148:149], v[250:251], v[190:191], v[148:149] op_sel:[0,1,0]
	v_add_f32_dpp v150, v150, v150 row_half_mirror row_mask:0xf bank_mask:0xf bound_ctrl:1
	v_add_f32_dpp v151, v151, v151 row_half_mirror row_mask:0xf bank_mask:0xf bound_ctrl:1
	s_nop 0
	s_waitcnt lgkmcnt(0)
; #define LAS __attribute__((address_space(3)))
; #define ROW16_SUM4(x, y, z, w) do { DPP4(x, y, z, w, "quad_perm:[1,0,3,2]", "s_nop 1"); DPP4(x, y, z, w, "quad_perm:[2,3,0,1]", ""); DPP4(x, y, z, w, "row_half_mirror", ""); DPP4(x, y, z, w, "row_mirror", ""); } while (0)
; template <bool SAMPLE>
; __device__ __forceinline__ void rwkv_unit(PR P, LAS float* lds, const int b, const int h, const int half, const int wv) {
;     ...
;                 for (int tt = 0; tt < GS; ++tt) {
;                     const LAS float* qn = q0 + (tt + 1 < GS ? tt + 1 : tt) * 384;
;                     const f32x4 nr4 = *(const LAS f32x4*)(qn + j0), no4 = *(const LAS f32x4*)(qn + 64 + j0), nk4 = *(const LAS f32x4*)(qn + 128 + j0), na4 = *(const LAS f32x4*)(qn + 192 + j0), nb4 = *(const LAS f32x4*)(qn + 256 + j0);
;                     const f32x2 nv2 = *(const LAS f32x2*)(qn + 320 + row0);
;                     f32x2 sa = (S[0] * a4[0] + S[1] * a4[1]) + (S[2] * a4[2] + S[3] * a4[3]);
;                     float sx = sa.x, sy = sa.y; ROW16_SUM4(sx, sy, py0, py1); sa = (f32x2){sx, sy};
;                     if (tt > 0) { yk0 = cgl == tt - 1 ? py0 : yk0; yk1 = cgl == tt - 1 ? py1 : yk1; }
; #pragma unroll
;                     for (int c = 0; c < 4; ++c) { f32x2 t = S[c] - S[c] * o4[c]; t = t + sa * b4[c]; S[c] = t + v2 * k4[c]; }
;                     const f32x2 y = (S[0] * r4[0] + S[1] * r4[1]) + (S[2] * r4[2] + S[3] * r4[3]);
;                     py0 = y.x; py1 = y.y;
;                     r4 = nr4; o4 = no4; k4 = nk4; a4 = na4; b4 = nb4; v2 = nv2;
	v_add_f32_dpp v150, v150, v150 row_mirror row_mask:0xf bank_mask:0xf bound_ctrl:1
	v_add_f32_dpp v151, v151, v151 row_mirror row_mask:0xf bank_mask:0xf bound_ctrl:1
	v_pk_fma_f32 v[66:67], v[150:151], v[196:197], v[142:143] op_sel_hi:[1,0,1]
	v_pk_fma_f32 v[20:21], v[150:151], v[196:197], v[144:145] op_sel:[0,1,0]
	v_pk_fma_f32 v[68:69], v[150:151], v[198:199], v[146:147] op_sel_hi:[1,0,1]
	v_pk_fma_f32 v[70:71], v[150:151], v[198:199], v[148:149] op_sel:[0,1,0]
	v_pk_mul_f32 v[136:137], v[66:67], v[180:181] op_sel_hi:[1,0]
	v_pk_mul_f32 v[150:151], v[66:67], v[212:213] op_sel_hi:[1,0]
	v_pk_fma_f32 v[142:143], v[66:67], v[204:205], v[66:67] op_sel_hi:[1,0,1] neg_lo:[1,0,0] neg_hi:[1,0,0]
	v_pk_fma_f32 v[136:137], v[20:21], v[180:181], v[136:137] op_sel:[0,1,0]
	v_pk_fma_f32 v[150:151], v[20:21], v[212:213], v[150:151] op_sel:[0,1,0]
	v_pk_fma_f32 v[144:145], v[20:21], v[204:205], v[20:21] op_sel:[0,1,0] neg_lo:[1,0,0] neg_hi:[1,0,0]
	v_pk_fma_f32 v[136:137], v[68:69], v[182:183], v[136:137] op_sel_hi:[1,0,1]
	v_pk_fma_f32 v[150:151], v[68:69], v[214:215], v[150:151] op_sel_hi:[1,0,1]
	v_pk_fma_f32 v[146:147], v[68:69], v[206:207], v[68:69] op_sel_hi:[1,0,1] neg_lo:[1,0,0] neg_hi:[1,0,0]
	v_pk_fma_f32 v[136:137], v[70:71], v[182:183], v[136:137] op_sel:[0,1,0]
	v_pk_fma_f32 v[150:151], v[70:71], v[214:215], v[150:151] op_sel:[0,1,0]
	v_pk_fma_f32 v[148:149], v[70:71], v[206:207], v[70:71] op_sel:[0,1,0] neg_lo:[1,0,0] neg_hi:[1,0,0]
	v_pk_fma_f32 v[142:143], v[240:241], v[208:209], v[142:143] op_sel_hi:[1,0,1]
	v_pk_fma_f32 v[144:145], v[240:241], v[208:209], v[144:145] op_sel:[0,1,0]
	v_add_f32_dpp v150, v150, v150 quad_perm:[1,0,3,2] row_mask:0xf bank_mask:0xf bound_ctrl:1
	v_add_f32_dpp v151, v151, v151 quad_perm:[1,0,3,2] row_mask:0xf bank_mask:0xf bound_ctrl:1
	v_pk_fma_f32 v[146:147], v[240:241], v[210:211], v[146:147] op_sel_hi:[1,0,1]
	v_add_f32_dpp v150, v150, v150 quad_perm:[2,3,0,1] row_mask:0xf bank_mask:0xf bound_ctrl:1
	v_add_f32_dpp v151, v151, v151 quad_perm:[2,3,0,1] row_mask:0xf bank_mask:0xf bound_ctrl:1
	v_pk_fma_f32 v[148:149], v[240:241], v[210:211], v[148:149] op_sel:[0,1,0]
	v_add_f32_dpp v150, v150, v150 row_half_mirror row_mask:0xf bank_mask:0xf bound_ctrl:1
	v_add_f32_dpp v151, v151, v151 row_half_mirror row_mask:0xf bank_mask:0xf bound_ctrl:1
	s_nop 0
	s_nop 0
	v_add_f32_dpp v150, v150, v150 row_mirror row_mask:0xf bank_mask:0xf bound_ctrl:1
	v_add_f32_dpp v151, v151, v151 row_mirror row_mask:0xf bank_mask:0xf bound_ctrl:1
	v_pk_fma_f32 v[66:67], v[150:151], v[216:217], v[142:143] op_sel_hi:[1,0,1]
	v_pk_fma_f32 v[20:21], v[150:151], v[216:217], v[144:145] op_sel:[0,1,0]
	v_pk_fma_f32 v[68:69], v[150:151], v[218:219], v[146:147] op_sel_hi:[1,0,1]
	v_pk_fma_f32 v[70:71], v[150:151], v[218:219], v[148:149] op_sel:[0,1,0]
	v_pk_mul_f32 v[138:139], v[66:67], v[200:201] op_sel_hi:[1,0]
	v_pk_mul_f32 v[150:151], v[66:67], v[232:233] op_sel_hi:[1,0]
	v_pk_fma_f32 v[142:143], v[66:67], v[224:225], v[66:67] op_sel_hi:[1,0,1] neg_lo:[1,0,0] neg_hi:[1,0,0]
	v_pk_fma_f32 v[138:139], v[20:21], v[200:201], v[138:139] op_sel:[0,1,0]
	v_pk_fma_f32 v[150:151], v[20:21], v[232:233], v[150:151] op_sel:[0,1,0]
	v_pk_fma_f32 v[144:145], v[20:21], v[224:225], v[20:21] op_sel:[0,1,0] neg_lo:[1,0,0] neg_hi:[1,0,0]
	v_pk_fma_f32 v[138:139], v[68:69], v[202:203], v[138:139] op_sel_hi:[1,0,1]
	v_pk_fma_f32 v[150:151], v[68:69], v[234:235], v[150:151] op_sel_hi:[1,0,1]
	v_pk_fma_f32 v[146:147], v[68:69], v[226:227], v[68:69] op_sel_hi:[1,0,1] neg_lo:[1,0,0] neg_hi:[1,0,0]
	v_pk_fma_f32 v[138:139], v[70:71], v[202:203], v[138:139] op_sel:[0,1,0]
	v_pk_fma_f32 v[150:151], v[70:71], v[234:235], v[150:151] op_sel:[0,1,0]
	v_pk_fma_f32 v[148:149], v[70:71], v[226:227], v[70:71] op_sel:[0,1,0] neg_lo:[1,0,0] neg_hi:[1,0,0]
	v_pk_fma_f32 v[142:143], v[242:243], v[228:229], v[142:143] op_sel_hi:[1,0,1]
	v_pk_fma_f32 v[144:145], v[242:243], v[228:229], v[144:145] op_sel:[0,1,0]
	v_add_f32_dpp v150, v150, v150 quad_perm:[1,0,3,2] row_mask:0xf bank_mask:0xf bound_ctrl:1
	v_add_f32_dpp v151, v151, v151 quad_perm:[1,0,3,2] row_mask:0xf bank_mask:0xf bound_ctrl:1
	v_pk_fma_f32 v[146:147], v[242:243], v[230:231], v[146:147] op_sel_hi:[1,0,1]
	v_add_f32_dpp v150, v150, v150 quad_perm:[2,3,0,1] row_mask:0xf bank_mask:0xf bound_ctrl:1
	v_add_f32_dpp v151, v151, v151 quad_perm:[2,3,0,1] row_mask:0xf bank_mask:0xf bound_ctrl:1
	v_pk_fma_f32 v[148:149], v[242:243], v[230:231], v[148:149] op_sel:[0,1,0]
	v_add_f32_dpp v150, v150, v150 row_half_mirror row_mask:0xf bank_mask:0xf bound_ctrl:1
	v_add_f32_dpp v151, v151, v151 row_half_mirror row_mask:0xf bank_mask:0xf bound_ctrl:1
	s_nop 0
	s_nop 0
	v_add_f32_dpp v150, v150, v150 row_mirror row_mask:0xf bank_mask:0xf bound_ctrl:1
	v_add_f32_dpp v151, v151, v151 row_mirror row_mask:0xf bank_mask:0xf bound_ctrl:1
	v_pk_fma_f32 v[66:67], v[150:151], v[236:237], v[142:143] op_sel_hi:[1,0,1]
	v_pk_fma_f32 v[20:21], v[150:151], v[236:237], v[144:145] op_sel:[0,1,0]
	v_pk_fma_f32 v[68:69], v[150:151], v[238:239], v[146:147] op_sel_hi:[1,0,1]
	v_pk_fma_f32 v[70:71], v[150:151], v[238:239], v[148:149] op_sel:[0,1,0]
	v_pk_mul_f32 v[140:141], v[66:67], v[220:221] op_sel_hi:[1,0]
	v_pk_fma_f32 v[140:141], v[20:21], v[220:221], v[140:141] op_sel:[0,1,0]
	v_pk_fma_f32 v[140:141], v[68:69], v[222:223], v[140:141] op_sel_hi:[1,0,1]
	v_pk_fma_f32 v[140:141], v[70:71], v[222:223], v[140:141] op_sel:[0,1,0]
	s_branch .LBB0_704
